# static s_setprio 1 for waves 4-7 at kernel entry, every per-phase s_setprio flip in the GEMM loops deleted (scan recurrence waves keep prio 3)
# speedup vs baseline: 1.0050x; 1.0021x over previous
.LBB0_8:
	s_or_b64 exec, exec, s[4:5]
	v_readlane_b32 s4, v255, 0
	s_load_dwordx16 s[68:83], s[0:1], 0x0
	s_lshr_b32 s5, s4, 6
	s_lshl_b32 s4, s2, 3
	s_add_i32 s34, s5, s4
	s_lshl_b32 s84, s3, 3
	s_add_u32 s10, s28, 0x8b00000
	s_mul_i32 s4, s5, 0x4100
	v_and_b32_e32 v178, 63, v0
	s_addc_u32 s11, s29, 0
	v_writelane_b32 v255, s5, 5
	s_add_i32 s4, s4, 0
	s_mov_b32 s13, 0
	v_writelane_b32 v255, s4, 6
	s_cmp_lt_u32 s5, 4
	s_cbranch_scc1 .Lprio_older
	s_setprio 1
.Lprio_older:
	s_cmpk_gt_i32 s34, 0x57f
	v_lshrrev_b32_e32 v166, 4, v178
	v_lshlrev_b32_e32 v202, 2, v0
	v_lshrrev_b32_e32 v209, 3, v178
	s_cbranch_scc1 .LBB0_131
	s_movk_i32 s4, 0x104
	v_mov_b32_e32 v3, 0x410
	v_mad_u32_u24 v23, v166, s4, v3
	v_mov_b32_e32 v3, 0x820
	v_mad_u32_u24 v25, v166, s4, v3
	v_mov_b32_e32 v3, 0xc30
	v_mad_u32_u24 v27, v166, s4, v3
	v_mov_b32_e32 v3, 0x1040
	v_mad_u32_u24 v29, v166, s4, v3
	v_mov_b32_e32 v3, 0x1450
	v_mad_u32_u24 v31, v166, s4, v3
	v_mov_b32_e32 v3, 0x1860
	v_mad_u32_u24 v33, v166, s4, v3
	v_mov_b32_e32 v3, 0x1c70
	v_mad_u32_u24 v35, v166, s4, v3
	v_lshlrev_b32_e32 v3, 3, v0
	s_waitcnt lgkmcnt(0)
	s_cmp_lg_u64 s[72:73], 0
	v_and_b32_e32 v3, 56, v3
	v_and_b32_e32 v1, 60, v202
	s_cselect_b64 s[14:15], -1, 0
	v_readlane_b32 s5, v255, 6
	v_mov_b32_e32 v2, 0
	v_mul_u32_u24_e32 v8, 0x104, v3
	v_lshlrev_b32_e32 v6, 1, v3
	v_lshlrev_b32_e32 v3, 2, v209
	v_lshlrev_b32_e32 v4, 2, v1
	v_mov_b32_e32 v5, v2
	v_mov_b32_e32 v7, v2
	v_add3_u32 v44, s5, v8, v3
	v_cndmask_b32_e64 v3, 0, 1, s[14:15]
	v_add_u32_e32 v20, s5, v4
	v_lshl_add_u64 v[12:13], s[76:77], 0, v[4:5]
	v_mul_u32_u24_e32 v21, 0x104, v166
	v_or_b32_e32 v22, 4, v166
	v_or_b32_e32 v24, 8, v166
	v_or_b32_e32 v26, 12, v166
	v_or_b32_e32 v28, 16, v166
	v_or_b32_e32 v30, 20, v166
	v_or_b32_e32 v32, 24, v166
	v_or_b32_e32 v34, 28, v166
	v_or_b32_e32 v36, 32, v166
	v_or_b32_e32 v37, 36, v166
	v_or_b32_e32 v38, 40, v166
	v_or_b32_e32 v39, 44, v166
	v_or_b32_e32 v40, 48, v166
	v_or_b32_e32 v41, 52, v166
	v_or_b32_e32 v42, 56, v166
	v_or_b32_e32 v43, 60, v166
	v_lshl_add_u64 v[14:15], s[10:11], 0, v[6:7]
	v_or_b32_e32 v45, 8, v209
	v_or_b32_e32 v46, 16, v209
	v_or_b32_e32 v47, 24, v209
	v_or_b32_e32 v48, 32, v209
	v_or_b32_e32 v49, 40, v209
	v_or_b32_e32 v50, 48, v209
	v_or_b32_e32 v51, 56, v209
	v_lshl_add_u64 v[16:17], s[74:75], 0, v[4:5]
	v_mov_b32_e32 v167, v2
	s_lshl_b32 s20, s34, 6
	s_lshl_b32 s21, s84, 6
	s_lshl_b32 s22, s34, 7
	s_lshl_b32 s23, s84, 7
	s_movk_i32 s24, 0xb00
	v_cmp_ne_u32_e64 s[8:9], 1, v3
	s_movk_i32 s25, 0x2c00
	s_mov_b32 s26, s34
	s_branch .LBB0_12

.LBB0_233:
	ds_read_b128 v[140:143], v170
	ds_read_b128 v[180:183], v170 offset:1024
	ds_read_b128 v[184:187], v170 offset:2048
	ds_read_b128 v[188:191], v170 offset:3072
	ds_read_b128 v[192:195], v171
	ds_read_b128 v[196:199], v171 offset:1024
	ds_read_b128 v[204:207], v171 offset:2048
	ds_read_b128 v[212:215], v171 offset:3072
	s_add_u32 s76, vcc_lo, 0xfffc0080
	s_addc_u32 s77, vcc_hi, -1
	s_cmp_eq_u32 s93, 12
	s_cselect_b32 s97, s6, s77
	s_cselect_b32 s96, s7, s76
	s_cselect_b32 s87, s75, s92
	s_cselect_b32 s86, s91, s95
	v_lshl_add_u64 v[144:145], vcc, 0, v[132:133]
	s_add_i32 m0, s54, 0xc000
	ds_read_b128 v[216:219], v172
	ds_read_b128 v[220:223], v172 offset:1024
	ds_read_b128 v[224:227], v172 offset:2048
	ds_read_b128 v[228:231], v172 offset:3072
	ds_read_b128 v[232:235], v172 offset:4096
	ds_read_b128 v[236:239], v172 offset:5120
	ds_read_b128 v[240:243], v172 offset:6144
	ds_read_b128 v[244:247], v172 offset:7168
	global_load_lds_dwordx4 v[144:145], off
	v_lshl_add_u64 v[144:145], vcc, 0, v[134:135]
	s_add_i32 m0, s54, 0xe000
	s_nop 0
	global_load_lds_dwordx4 v[144:145], off
	s_waitcnt vmcnt(8)
	s_waitcnt lgkmcnt(0)
	s_barrier
	s_waitcnt lgkmcnt(0)
	v_mfma_f32_16x16x32_bf16 v[126:129], v[140:143], v[216:219], v[126:129]
	v_mfma_f32_16x16x32_bf16 v[122:125], v[184:187], v[216:219], v[122:125]
	v_mfma_f32_16x16x32_bf16 v[110:113], v[140:143], v[224:227], v[110:113]
	v_mfma_f32_16x16x32_bf16 v[106:109], v[184:187], v[224:227], v[106:109]
	v_mfma_f32_16x16x32_bf16 v[94:97], v[140:143], v[232:235], v[94:97]
	v_mfma_f32_16x16x32_bf16 v[90:93], v[184:187], v[232:235], v[90:93]
	v_mfma_f32_16x16x32_bf16 v[78:81], v[140:143], v[240:243], v[78:81]
	v_mfma_f32_16x16x32_bf16 v[74:77], v[184:187], v[240:243], v[74:77]
	v_mfma_f32_16x16x32_bf16 v[126:129], v[180:183], v[220:223], v[126:129]
	v_mfma_f32_16x16x32_bf16 v[122:125], v[188:191], v[220:223], v[122:125]
	v_mfma_f32_16x16x32_bf16 v[110:113], v[180:183], v[228:231], v[110:113]
	v_mfma_f32_16x16x32_bf16 v[106:109], v[188:191], v[228:231], v[106:109]
	v_mfma_f32_16x16x32_bf16 v[94:97], v[180:183], v[236:239], v[94:97]
	v_mfma_f32_16x16x32_bf16 v[90:93], v[188:191], v[236:239], v[90:93]
	v_mfma_f32_16x16x32_bf16 v[78:81], v[180:183], v[244:247], v[78:81]
	v_mfma_f32_16x16x32_bf16 v[74:77], v[188:191], v[244:247], v[74:77]
	v_mfma_f32_16x16x32_bf16 v[118:121], v[192:195], v[216:219], v[118:121]
	v_mfma_f32_16x16x32_bf16 v[114:117], v[204:207], v[216:219], v[114:117]
	v_mfma_f32_16x16x32_bf16 v[102:105], v[192:195], v[224:227], v[102:105]
	v_mfma_f32_16x16x32_bf16 v[98:101], v[204:207], v[224:227], v[98:101]
	v_mfma_f32_16x16x32_bf16 v[86:89], v[192:195], v[232:235], v[86:89]
	v_mfma_f32_16x16x32_bf16 v[82:85], v[204:207], v[232:235], v[82:85]
	v_mfma_f32_16x16x32_bf16 v[70:73], v[192:195], v[240:243], v[70:73]
	v_mfma_f32_16x16x32_bf16 v[66:69], v[204:207], v[240:243], v[66:69]
	v_mfma_f32_16x16x32_bf16 v[118:121], v[196:199], v[220:223], v[118:121]
	v_mfma_f32_16x16x32_bf16 v[114:117], v[212:215], v[220:223], v[114:117]
	v_mfma_f32_16x16x32_bf16 v[102:105], v[196:199], v[228:231], v[102:105]
	v_mfma_f32_16x16x32_bf16 v[98:101], v[212:215], v[228:231], v[98:101]
	v_mfma_f32_16x16x32_bf16 v[86:89], v[196:199], v[236:239], v[86:89]
	v_mfma_f32_16x16x32_bf16 v[82:85], v[212:215], v[236:239], v[82:85]
	v_mfma_f32_16x16x32_bf16 v[70:73], v[196:199], v[244:247], v[70:73]
	v_mfma_f32_16x16x32_bf16 v[66:69], v[212:215], v[244:247], v[66:69]
	s_barrier
	s_add_i32 s76, s85, s35
	v_lshl_add_u64 v[144:145], s[86:87], 0, v[148:149]
	s_mov_b32 m0, s76
	ds_read_b128 v[216:219], v172 offset:16384
	ds_read_b128 v[220:223], v172 offset:17408
	ds_read_b128 v[224:227], v172 offset:18432
	ds_read_b128 v[228:231], v172 offset:19456
	ds_read_b128 v[232:235], v172 offset:20480
	ds_read_b128 v[236:239], v172 offset:21504
	ds_read_b128 v[240:243], v172 offset:22528
	ds_read_b128 v[244:247], v172 offset:23552
	global_load_lds_dwordx4 v[144:145], off
	s_add_i32 m0, s76, 0x2000
	s_add_u32 s76, s86, 0x40000
	v_lshl_add_u64 v[176:177], s[86:87], 0, v[152:153]
	s_addc_u32 s77, s87, 0
	s_add_i32 s33, s88, s35
	global_load_lds_dwordx4 v[176:177], off
	v_lshl_add_u64 v[248:249], s[76:77], 0, v[148:149]
	s_mov_b32 m0, s33
	v_lshl_add_u64 v[250:251], s[96:97], 0, v[150:151]
	global_load_lds_dwordx4 v[248:249], off
	v_lshl_add_u64 v[248:249], s[76:77], 0, v[152:153]
	s_add_i32 m0, s33, 0x2000
	s_nop 0
	global_load_lds_dwordx4 v[248:249], off
	v_lshl_add_u64 v[248:249], s[96:97], 0, v[146:147]
	s_mov_b32 m0, s54
	s_nop 0
	global_load_lds_dwordx4 v[248:249], off
	s_mov_b32 m0, s55
	s_nop 0
	global_load_lds_dwordx4 v[250:251], off
	s_waitcnt vmcnt(8)
	s_waitcnt lgkmcnt(0)
	s_barrier
	s_waitcnt lgkmcnt(0)
	v_mfma_f32_16x16x32_bf16 v[62:65], v[140:143], v[216:219], v[62:65]
	v_mfma_f32_16x16x32_bf16 v[58:61], v[184:187], v[216:219], v[58:61]
	v_mfma_f32_16x16x32_bf16 v[46:49], v[140:143], v[224:227], v[46:49]
	v_mfma_f32_16x16x32_bf16 v[42:45], v[184:187], v[224:227], v[42:45]
	v_mfma_f32_16x16x32_bf16 v[30:33], v[140:143], v[232:235], v[30:33]
	v_mfma_f32_16x16x32_bf16 v[26:29], v[184:187], v[232:235], v[26:29]
	v_mfma_f32_16x16x32_bf16 v[14:17], v[140:143], v[240:243], v[14:17]
	v_mfma_f32_16x16x32_bf16 v[10:13], v[184:187], v[240:243], v[10:13]
	v_mfma_f32_16x16x32_bf16 v[62:65], v[180:183], v[220:223], v[62:65]
	v_mfma_f32_16x16x32_bf16 v[58:61], v[188:191], v[220:223], v[58:61]
	v_mfma_f32_16x16x32_bf16 v[46:49], v[180:183], v[228:231], v[46:49]
	v_mfma_f32_16x16x32_bf16 v[42:45], v[188:191], v[228:231], v[42:45]
	v_mfma_f32_16x16x32_bf16 v[30:33], v[180:183], v[236:239], v[30:33]
	v_mfma_f32_16x16x32_bf16 v[26:29], v[188:191], v[236:239], v[26:29]
	v_mfma_f32_16x16x32_bf16 v[14:17], v[180:183], v[244:247], v[14:17]
	v_mfma_f32_16x16x32_bf16 v[10:13], v[188:191], v[244:247], v[10:13]
	v_mfma_f32_16x16x32_bf16 v[54:57], v[192:195], v[216:219], v[54:57]
	v_mfma_f32_16x16x32_bf16 v[50:53], v[204:207], v[216:219], v[50:53]
	v_mfma_f32_16x16x32_bf16 v[38:41], v[192:195], v[224:227], v[38:41]
	v_mfma_f32_16x16x32_bf16 v[34:37], v[204:207], v[224:227], v[34:37]
	v_mfma_f32_16x16x32_bf16 v[22:25], v[192:195], v[232:235], v[22:25]
	v_mfma_f32_16x16x32_bf16 v[18:21], v[204:207], v[232:235], v[18:21]
	v_mfma_f32_16x16x32_bf16 v[6:9], v[192:195], v[240:243], v[6:9]
	v_mfma_f32_16x16x32_bf16 v[2:5], v[204:207], v[240:243], v[2:5]
	v_mfma_f32_16x16x32_bf16 v[54:57], v[196:199], v[220:223], v[54:57]
	v_mfma_f32_16x16x32_bf16 v[50:53], v[212:215], v[220:223], v[50:53]
	v_mfma_f32_16x16x32_bf16 v[38:41], v[196:199], v[228:231], v[38:41]
	v_mfma_f32_16x16x32_bf16 v[34:37], v[212:215], v[228:231], v[34:37]
	v_mfma_f32_16x16x32_bf16 v[22:25], v[196:199], v[236:239], v[22:25]
	v_mfma_f32_16x16x32_bf16 v[18:21], v[212:215], v[236:239], v[18:21]
	v_mfma_f32_16x16x32_bf16 v[6:9], v[196:199], v[244:247], v[6:9]
	v_mfma_f32_16x16x32_bf16 v[2:5], v[212:215], v[244:247], v[2:5]
	s_barrier
	s_add_i32 s33, 0, 0x18000
	v_add_u32_e32 v175, s33, v163
	s_add_i32 s53, 0, 0x1c000
	ds_read_b128 v[140:143], v175
	ds_read_b128 v[180:183], v175 offset:1024
	ds_read_b128 v[184:187], v175 offset:2048
	ds_read_b128 v[188:191], v175 offset:3072
	v_add_u32_e32 v175, s53, v163
	ds_read_b128 v[192:195], v175
	ds_read_b128 v[196:199], v175 offset:1024
	ds_read_b128 v[204:207], v175 offset:2048
	ds_read_b128 v[212:215], v175 offset:3072
	s_add_u32 s76, s96, 0x40000
	s_addc_u32 s77, s97, 0
	s_mov_b32 m0, s59
	v_lshl_add_u64 v[252:253], s[76:77], 0, v[146:147]
	ds_read_b128 v[216:219], v172 offset:32768
	ds_read_b128 v[220:223], v172 offset:33792
	ds_read_b128 v[224:227], v172 offset:34816
	ds_read_b128 v[228:231], v172 offset:35840
	ds_read_b128 v[232:235], v172 offset:36864
	ds_read_b128 v[236:239], v172 offset:37888
	ds_read_b128 v[240:243], v172 offset:38912
	ds_read_b128 v[244:247], v172 offset:39936
	global_load_lds_dwordx4 v[252:253], off
	v_lshl_add_u64 v[252:253], s[76:77], 0, v[150:151]
	s_mov_b32 m0, s61
	s_nop 0
	global_load_lds_dwordx4 v[252:253], off
	s_waitcnt vmcnt(8)
	s_waitcnt lgkmcnt(0)
	s_barrier
	s_waitcnt lgkmcnt(0)
	v_mfma_f32_16x16x32_bf16 v[126:129], v[140:143], v[216:219], v[126:129]
	v_mfma_f32_16x16x32_bf16 v[122:125], v[184:187], v[216:219], v[122:125]
	v_mfma_f32_16x16x32_bf16 v[110:113], v[140:143], v[224:227], v[110:113]
	v_mfma_f32_16x16x32_bf16 v[106:109], v[184:187], v[224:227], v[106:109]
	v_mfma_f32_16x16x32_bf16 v[94:97], v[140:143], v[232:235], v[94:97]
	v_mfma_f32_16x16x32_bf16 v[90:93], v[184:187], v[232:235], v[90:93]
	v_mfma_f32_16x16x32_bf16 v[78:81], v[140:143], v[240:243], v[78:81]
	v_mfma_f32_16x16x32_bf16 v[74:77], v[184:187], v[240:243], v[74:77]
	v_mfma_f32_16x16x32_bf16 v[126:129], v[180:183], v[220:223], v[126:129]
	v_mfma_f32_16x16x32_bf16 v[122:125], v[188:191], v[220:223], v[122:125]
	v_mfma_f32_16x16x32_bf16 v[110:113], v[180:183], v[228:231], v[110:113]
	v_mfma_f32_16x16x32_bf16 v[106:109], v[188:191], v[228:231], v[106:109]
	v_mfma_f32_16x16x32_bf16 v[94:97], v[180:183], v[236:239], v[94:97]
	v_mfma_f32_16x16x32_bf16 v[90:93], v[188:191], v[236:239], v[90:93]
	v_mfma_f32_16x16x32_bf16 v[78:81], v[180:183], v[244:247], v[78:81]
	v_mfma_f32_16x16x32_bf16 v[74:77], v[188:191], v[244:247], v[74:77]
	v_mfma_f32_16x16x32_bf16 v[118:121], v[192:195], v[216:219], v[118:121]
	v_mfma_f32_16x16x32_bf16 v[114:117], v[204:207], v[216:219], v[114:117]
	v_mfma_f32_16x16x32_bf16 v[102:105], v[192:195], v[224:227], v[102:105]
	v_mfma_f32_16x16x32_bf16 v[98:101], v[204:207], v[224:227], v[98:101]
	v_mfma_f32_16x16x32_bf16 v[86:89], v[192:195], v[232:235], v[86:89]
	v_mfma_f32_16x16x32_bf16 v[82:85], v[204:207], v[232:235], v[82:85]
	v_mfma_f32_16x16x32_bf16 v[70:73], v[192:195], v[240:243], v[70:73]
	v_mfma_f32_16x16x32_bf16 v[66:69], v[204:207], v[240:243], v[66:69]
	v_mfma_f32_16x16x32_bf16 v[118:121], v[196:199], v[220:223], v[118:121]
	v_mfma_f32_16x16x32_bf16 v[114:117], v[212:215], v[220:223], v[114:117]
	v_mfma_f32_16x16x32_bf16 v[102:105], v[196:199], v[228:231], v[102:105]
	v_mfma_f32_16x16x32_bf16 v[98:101], v[212:215], v[228:231], v[98:101]
	v_mfma_f32_16x16x32_bf16 v[86:89], v[196:199], v[236:239], v[86:89]
	v_mfma_f32_16x16x32_bf16 v[82:85], v[212:215], v[236:239], v[82:85]
	v_mfma_f32_16x16x32_bf16 v[70:73], v[196:199], v[244:247], v[70:73]
	v_mfma_f32_16x16x32_bf16 v[66:69], v[212:215], v[244:247], v[66:69]
	s_barrier
	s_add_i32 s33, s33, s35
	v_lshl_add_u64 v[144:145], v[144:145], 0, s[42:43]
	s_mov_b32 m0, s33
	ds_read_b128 v[216:219], v172 offset:49152
	ds_read_b128 v[220:223], v172 offset:50176
	ds_read_b128 v[224:227], v172 offset:51200
	ds_read_b128 v[228:231], v172 offset:52224
	ds_read_b128 v[232:235], v172 offset:53248
	ds_read_b128 v[236:239], v172 offset:54272
	ds_read_b128 v[240:243], v172 offset:55296
	ds_read_b128 v[244:247], v172 offset:56320
	global_load_lds_dwordx4 v[144:145], off
	s_add_i32 m0, s33, 0x2000
	s_add_u32 s76, s86, 0x40080
	v_lshl_add_u64 v[144:145], v[176:177], 0, s[42:43]
	s_addc_u32 s77, s87, 0
	s_add_i32 s33, s53, s35
	global_load_lds_dwordx4 v[144:145], off
	v_lshl_add_u64 v[144:145], s[76:77], 0, v[148:149]
	s_mov_b32 m0, s33
	s_nop 0
	global_load_lds_dwordx4 v[144:145], off
	v_lshl_add_u64 v[144:145], s[76:77], 0, v[152:153]
	s_add_i32 m0, s33, 0x2000
	s_nop 0
	global_load_lds_dwordx4 v[144:145], off
	v_lshl_add_u64 v[144:145], v[248:249], 0, s[42:43]
	s_mov_b32 m0, s65
	s_nop 0
	global_load_lds_dwordx4 v[144:145], off
	v_lshl_add_u64 v[144:145], v[250:251], 0, s[42:43]
	s_mov_b32 m0, s66
	s_nop 0
	global_load_lds_dwordx4 v[144:145], off
	s_waitcnt vmcnt(8)
	s_waitcnt lgkmcnt(0)
	s_barrier
	s_waitcnt lgkmcnt(0)
	v_mfma_f32_16x16x32_bf16 v[62:65], v[140:143], v[216:219], v[62:65]
	v_mfma_f32_16x16x32_bf16 v[58:61], v[184:187], v[216:219], v[58:61]
	v_mfma_f32_16x16x32_bf16 v[46:49], v[140:143], v[224:227], v[46:49]
	v_mfma_f32_16x16x32_bf16 v[42:45], v[184:187], v[224:227], v[42:45]
	v_mfma_f32_16x16x32_bf16 v[30:33], v[140:143], v[232:235], v[30:33]
	v_mfma_f32_16x16x32_bf16 v[26:29], v[184:187], v[232:235], v[26:29]
	v_mfma_f32_16x16x32_bf16 v[14:17], v[140:143], v[240:243], v[14:17]
	v_mfma_f32_16x16x32_bf16 v[10:13], v[184:187], v[240:243], v[10:13]
	v_mfma_f32_16x16x32_bf16 v[62:65], v[180:183], v[220:223], v[62:65]
	v_mfma_f32_16x16x32_bf16 v[58:61], v[188:191], v[220:223], v[58:61]
	v_mfma_f32_16x16x32_bf16 v[46:49], v[180:183], v[228:231], v[46:49]
	v_mfma_f32_16x16x32_bf16 v[42:45], v[188:191], v[228:231], v[42:45]
	v_mfma_f32_16x16x32_bf16 v[30:33], v[180:183], v[236:239], v[30:33]
	v_mfma_f32_16x16x32_bf16 v[26:29], v[188:191], v[236:239], v[26:29]
	v_mfma_f32_16x16x32_bf16 v[14:17], v[180:183], v[244:247], v[14:17]
	v_mfma_f32_16x16x32_bf16 v[10:13], v[188:191], v[244:247], v[10:13]
	v_mfma_f32_16x16x32_bf16 v[54:57], v[192:195], v[216:219], v[54:57]
	v_mfma_f32_16x16x32_bf16 v[50:53], v[204:207], v[216:219], v[50:53]
	v_mfma_f32_16x16x32_bf16 v[38:41], v[192:195], v[224:227], v[38:41]
	v_mfma_f32_16x16x32_bf16 v[34:37], v[204:207], v[224:227], v[34:37]
	v_mfma_f32_16x16x32_bf16 v[22:25], v[192:195], v[232:235], v[22:25]
	v_mfma_f32_16x16x32_bf16 v[18:21], v[204:207], v[232:235], v[18:21]
	v_mfma_f32_16x16x32_bf16 v[6:9], v[192:195], v[240:243], v[6:9]
	v_mfma_f32_16x16x32_bf16 v[2:5], v[204:207], v[240:243], v[2:5]
	v_mfma_f32_16x16x32_bf16 v[54:57], v[196:199], v[220:223], v[54:57]
	v_mfma_f32_16x16x32_bf16 v[50:53], v[212:215], v[220:223], v[50:53]
	v_mfma_f32_16x16x32_bf16 v[38:41], v[196:199], v[228:231], v[38:41]
	v_mfma_f32_16x16x32_bf16 v[34:37], v[212:215], v[228:231], v[34:37]
	v_mfma_f32_16x16x32_bf16 v[22:25], v[196:199], v[236:239], v[22:25]
	v_mfma_f32_16x16x32_bf16 v[18:21], v[212:215], v[236:239], v[18:21]
	v_mfma_f32_16x16x32_bf16 v[6:9], v[196:199], v[244:247], v[6:9]
	v_mfma_f32_16x16x32_bf16 v[2:5], v[212:215], v[244:247], v[2:5]
	s_barrier
	s_add_i32 s93, s93, 2
	s_add_u32 vcc_lo, vcc_lo, 0x100
	s_addc_u32 vcc_hi, vcc_hi, 0
	s_add_u32 s95, s95, 0x100
	s_addc_u32 s92, s92, 0
	s_cmp_gt_u32 s93, 13
	s_cbranch_scc0 .LBB0_233
	s_and_b64 vcc, exec, s[62:63]
	s_cbranch_vccz .LBB0_236
	s_barrier

.LBB0_446:
	ds_read_b128 v[138:141], v153
	ds_read_b128 v[142:145], v153 offset:1024
	ds_read_b128 v[174:177], v153 offset:2048
	ds_read_b128 v[182:185], v153 offset:3072
	ds_read_b128 v[186:189], v155
	ds_read_b128 v[190:193], v155 offset:1024
	ds_read_b128 v[194:197], v155 offset:2048
	ds_read_b128 v[212:215], v155 offset:3072
	s_add_u32 s30, s8, 0xfff50080
	s_addc_u32 s31, s9, -1
	s_cmp_eq_u32 s75, 40
	s_cselect_b32 s73, s83, s31
	s_cselect_b32 s72, s82, s30
	s_cselect_b32 s31, s87, s74
	s_cselect_b32 s30, s86, s67
	v_lshl_add_u64 v[170:171], s[8:9], 0, v[132:133]
	s_add_i32 m0, s11, 0xc000
	ds_read_b128 v[216:219], v165
	ds_read_b128 v[220:223], v165 offset:1024
	ds_read_b128 v[224:227], v165 offset:2048
	ds_read_b128 v[228:231], v165 offset:3072
	ds_read_b128 v[232:235], v165 offset:4096
	ds_read_b128 v[236:239], v165 offset:5120
	ds_read_b128 v[240:243], v165 offset:6144
	ds_read_b128 v[244:247], v165 offset:7168
	global_load_lds_dwordx4 v[170:171], off
	v_lshl_add_u64 v[170:171], s[8:9], 0, v[134:135]
	s_add_i32 m0, s11, 0xe000
	s_nop 0
	global_load_lds_dwordx4 v[170:171], off
	s_waitcnt vmcnt(8)
	s_waitcnt lgkmcnt(0)
	s_barrier
	s_waitcnt lgkmcnt(0)
	v_mfma_f32_16x16x32_bf16 v[126:129], v[138:141], v[216:219], v[126:129]
	v_mfma_f32_16x16x32_bf16 v[122:125], v[174:177], v[216:219], v[122:125]
	v_mfma_f32_16x16x32_bf16 v[110:113], v[138:141], v[224:227], v[110:113]
	v_mfma_f32_16x16x32_bf16 v[106:109], v[174:177], v[224:227], v[106:109]
	v_mfma_f32_16x16x32_bf16 v[94:97], v[138:141], v[232:235], v[94:97]
	v_mfma_f32_16x16x32_bf16 v[90:93], v[174:177], v[232:235], v[90:93]
	v_mfma_f32_16x16x32_bf16 v[78:81], v[138:141], v[240:243], v[78:81]
	v_mfma_f32_16x16x32_bf16 v[74:77], v[174:177], v[240:243], v[74:77]
	v_mfma_f32_16x16x32_bf16 v[126:129], v[142:145], v[220:223], v[126:129]
	v_mfma_f32_16x16x32_bf16 v[122:125], v[182:185], v[220:223], v[122:125]
	v_mfma_f32_16x16x32_bf16 v[110:113], v[142:145], v[228:231], v[110:113]
	v_mfma_f32_16x16x32_bf16 v[106:109], v[182:185], v[228:231], v[106:109]
	v_mfma_f32_16x16x32_bf16 v[94:97], v[142:145], v[236:239], v[94:97]
	v_mfma_f32_16x16x32_bf16 v[90:93], v[182:185], v[236:239], v[90:93]
	v_mfma_f32_16x16x32_bf16 v[78:81], v[142:145], v[244:247], v[78:81]
	v_mfma_f32_16x16x32_bf16 v[74:77], v[182:185], v[244:247], v[74:77]
	v_mfma_f32_16x16x32_bf16 v[118:121], v[186:189], v[216:219], v[118:121]
	v_mfma_f32_16x16x32_bf16 v[114:117], v[194:197], v[216:219], v[114:117]
	v_mfma_f32_16x16x32_bf16 v[102:105], v[186:189], v[224:227], v[102:105]
	v_mfma_f32_16x16x32_bf16 v[98:101], v[194:197], v[224:227], v[98:101]
	v_mfma_f32_16x16x32_bf16 v[86:89], v[186:189], v[232:235], v[86:89]
	v_mfma_f32_16x16x32_bf16 v[82:85], v[194:197], v[232:235], v[82:85]
	v_mfma_f32_16x16x32_bf16 v[70:73], v[186:189], v[240:243], v[70:73]
	v_mfma_f32_16x16x32_bf16 v[66:69], v[194:197], v[240:243], v[66:69]
	v_mfma_f32_16x16x32_bf16 v[118:121], v[190:193], v[220:223], v[118:121]
	v_mfma_f32_16x16x32_bf16 v[114:117], v[212:215], v[220:223], v[114:117]
	v_mfma_f32_16x16x32_bf16 v[102:105], v[190:193], v[228:231], v[102:105]
	v_mfma_f32_16x16x32_bf16 v[98:101], v[212:215], v[228:231], v[98:101]
	v_mfma_f32_16x16x32_bf16 v[86:89], v[190:193], v[236:239], v[86:89]
	v_mfma_f32_16x16x32_bf16 v[82:85], v[212:215], v[236:239], v[82:85]
	v_mfma_f32_16x16x32_bf16 v[70:73], v[190:193], v[244:247], v[70:73]
	v_mfma_f32_16x16x32_bf16 v[66:69], v[212:215], v[244:247], v[66:69]
	s_barrier
	s_add_i32 s33, s61, s10
	v_lshl_add_u64 v[170:171], s[30:31], 0, v[158:159]
	s_mov_b32 m0, s33
	ds_read_b128 v[216:219], v165 offset:16384
	ds_read_b128 v[220:223], v165 offset:17408
	ds_read_b128 v[224:227], v165 offset:18432
	ds_read_b128 v[228:231], v165 offset:19456
	ds_read_b128 v[232:235], v165 offset:20480
	ds_read_b128 v[236:239], v165 offset:21504
	ds_read_b128 v[240:243], v165 offset:22528
	ds_read_b128 v[244:247], v165 offset:23552
	global_load_lds_dwordx4 v[170:171], off
	s_add_i32 m0, s33, 0x2000
	s_add_u32 s76, s30, 0xb0000
	v_lshl_add_u64 v[198:199], s[30:31], 0, v[162:163]
	s_addc_u32 s77, s31, 0
	s_add_i32 s33, s64, s10
	global_load_lds_dwordx4 v[198:199], off
	v_lshl_add_u64 v[248:249], s[76:77], 0, v[158:159]
	s_mov_b32 m0, s33
	v_lshl_add_u64 v[250:251], s[72:73], 0, v[160:161]
	global_load_lds_dwordx4 v[248:249], off
	v_lshl_add_u64 v[248:249], s[76:77], 0, v[162:163]
	s_add_i32 m0, s33, 0x2000
	s_nop 0
	global_load_lds_dwordx4 v[248:249], off
	v_lshl_add_u64 v[248:249], s[72:73], 0, v[156:157]
	s_mov_b32 m0, s11
	s_nop 0
	global_load_lds_dwordx4 v[248:249], off
	s_mov_b32 m0, s35
	s_nop 0
	global_load_lds_dwordx4 v[250:251], off
	s_waitcnt vmcnt(8)
	s_waitcnt lgkmcnt(0)
	s_barrier
	s_waitcnt lgkmcnt(0)
	v_mfma_f32_16x16x32_bf16 v[62:65], v[138:141], v[216:219], v[62:65]
	v_mfma_f32_16x16x32_bf16 v[58:61], v[174:177], v[216:219], v[58:61]
	v_mfma_f32_16x16x32_bf16 v[46:49], v[138:141], v[224:227], v[46:49]
	v_mfma_f32_16x16x32_bf16 v[42:45], v[174:177], v[224:227], v[42:45]
	v_mfma_f32_16x16x32_bf16 v[30:33], v[138:141], v[232:235], v[30:33]
	v_mfma_f32_16x16x32_bf16 v[26:29], v[174:177], v[232:235], v[26:29]
	v_mfma_f32_16x16x32_bf16 v[14:17], v[138:141], v[240:243], v[14:17]
	v_mfma_f32_16x16x32_bf16 v[10:13], v[174:177], v[240:243], v[10:13]
	v_mfma_f32_16x16x32_bf16 v[62:65], v[142:145], v[220:223], v[62:65]
	v_mfma_f32_16x16x32_bf16 v[58:61], v[182:185], v[220:223], v[58:61]
	v_mfma_f32_16x16x32_bf16 v[46:49], v[142:145], v[228:231], v[46:49]
	v_mfma_f32_16x16x32_bf16 v[42:45], v[182:185], v[228:231], v[42:45]
	v_mfma_f32_16x16x32_bf16 v[30:33], v[142:145], v[236:239], v[30:33]
	v_mfma_f32_16x16x32_bf16 v[26:29], v[182:185], v[236:239], v[26:29]
	v_mfma_f32_16x16x32_bf16 v[14:17], v[142:145], v[244:247], v[14:17]
	v_mfma_f32_16x16x32_bf16 v[10:13], v[182:185], v[244:247], v[10:13]
	v_mfma_f32_16x16x32_bf16 v[54:57], v[186:189], v[216:219], v[54:57]
	v_mfma_f32_16x16x32_bf16 v[50:53], v[194:197], v[216:219], v[50:53]
	v_mfma_f32_16x16x32_bf16 v[38:41], v[186:189], v[224:227], v[38:41]
	v_mfma_f32_16x16x32_bf16 v[34:37], v[194:197], v[224:227], v[34:37]
	v_mfma_f32_16x16x32_bf16 v[22:25], v[186:189], v[232:235], v[22:25]
	v_mfma_f32_16x16x32_bf16 v[18:21], v[194:197], v[232:235], v[18:21]
	v_mfma_f32_16x16x32_bf16 v[6:9], v[186:189], v[240:243], v[6:9]
	v_mfma_f32_16x16x32_bf16 v[2:5], v[194:197], v[240:243], v[2:5]
	v_mfma_f32_16x16x32_bf16 v[54:57], v[190:193], v[220:223], v[54:57]
	v_mfma_f32_16x16x32_bf16 v[50:53], v[212:215], v[220:223], v[50:53]
	v_mfma_f32_16x16x32_bf16 v[38:41], v[190:193], v[228:231], v[38:41]
	v_mfma_f32_16x16x32_bf16 v[34:37], v[212:215], v[228:231], v[34:37]
	v_mfma_f32_16x16x32_bf16 v[22:25], v[190:193], v[236:239], v[22:25]
	v_mfma_f32_16x16x32_bf16 v[18:21], v[212:215], v[236:239], v[18:21]
	v_mfma_f32_16x16x32_bf16 v[6:9], v[190:193], v[244:247], v[6:9]
	v_mfma_f32_16x16x32_bf16 v[2:5], v[212:215], v[244:247], v[2:5]
	s_barrier
	s_add_i32 s33, 0, 0x18000
	v_add_u32_e32 v181, s33, v149
	s_add_i32 s76, 0, 0x1c000
	ds_read_b128 v[138:141], v181
	ds_read_b128 v[142:145], v181 offset:1024
	ds_read_b128 v[174:177], v181 offset:2048
	ds_read_b128 v[182:185], v181 offset:3072
	v_add_u32_e32 v181, s76, v149
	ds_read_b128 v[186:189], v181
	ds_read_b128 v[190:193], v181 offset:1024
	ds_read_b128 v[194:197], v181 offset:2048
	ds_read_b128 v[212:215], v181 offset:3072
	s_add_u32 s72, s72, 0xb0000
	s_addc_u32 s73, s73, 0
	s_mov_b32 m0, s52
	v_lshl_add_u64 v[252:253], s[72:73], 0, v[156:157]
	ds_read_b128 v[216:219], v165 offset:32768
	ds_read_b128 v[220:223], v165 offset:33792
	ds_read_b128 v[224:227], v165 offset:34816
	ds_read_b128 v[228:231], v165 offset:35840
	ds_read_b128 v[232:235], v165 offset:36864
	ds_read_b128 v[236:239], v165 offset:37888
	ds_read_b128 v[240:243], v165 offset:38912
	ds_read_b128 v[244:247], v165 offset:39936
	global_load_lds_dwordx4 v[252:253], off
	v_lshl_add_u64 v[252:253], s[72:73], 0, v[160:161]
	s_mov_b32 m0, s53
	s_nop 0
	global_load_lds_dwordx4 v[252:253], off
	s_waitcnt vmcnt(8)
	s_waitcnt lgkmcnt(0)
	s_barrier
	s_waitcnt lgkmcnt(0)
	v_mfma_f32_16x16x32_bf16 v[126:129], v[138:141], v[216:219], v[126:129]
	v_mfma_f32_16x16x32_bf16 v[122:125], v[174:177], v[216:219], v[122:125]
	v_mfma_f32_16x16x32_bf16 v[110:113], v[138:141], v[224:227], v[110:113]
	v_mfma_f32_16x16x32_bf16 v[106:109], v[174:177], v[224:227], v[106:109]
	v_mfma_f32_16x16x32_bf16 v[94:97], v[138:141], v[232:235], v[94:97]
	v_mfma_f32_16x16x32_bf16 v[90:93], v[174:177], v[232:235], v[90:93]
	v_mfma_f32_16x16x32_bf16 v[78:81], v[138:141], v[240:243], v[78:81]
	v_mfma_f32_16x16x32_bf16 v[74:77], v[174:177], v[240:243], v[74:77]
	v_mfma_f32_16x16x32_bf16 v[126:129], v[142:145], v[220:223], v[126:129]
	v_mfma_f32_16x16x32_bf16 v[122:125], v[182:185], v[220:223], v[122:125]
	v_mfma_f32_16x16x32_bf16 v[110:113], v[142:145], v[228:231], v[110:113]
	v_mfma_f32_16x16x32_bf16 v[106:109], v[182:185], v[228:231], v[106:109]
	v_mfma_f32_16x16x32_bf16 v[94:97], v[142:145], v[236:239], v[94:97]
	v_mfma_f32_16x16x32_bf16 v[90:93], v[182:185], v[236:239], v[90:93]
	v_mfma_f32_16x16x32_bf16 v[78:81], v[142:145], v[244:247], v[78:81]
	v_mfma_f32_16x16x32_bf16 v[74:77], v[182:185], v[244:247], v[74:77]
	v_mfma_f32_16x16x32_bf16 v[118:121], v[186:189], v[216:219], v[118:121]
	v_mfma_f32_16x16x32_bf16 v[114:117], v[194:197], v[216:219], v[114:117]
	v_mfma_f32_16x16x32_bf16 v[102:105], v[186:189], v[224:227], v[102:105]
	v_mfma_f32_16x16x32_bf16 v[98:101], v[194:197], v[224:227], v[98:101]
	v_mfma_f32_16x16x32_bf16 v[86:89], v[186:189], v[232:235], v[86:89]
	v_mfma_f32_16x16x32_bf16 v[82:85], v[194:197], v[232:235], v[82:85]
	v_mfma_f32_16x16x32_bf16 v[70:73], v[186:189], v[240:243], v[70:73]
	v_mfma_f32_16x16x32_bf16 v[66:69], v[194:197], v[240:243], v[66:69]
	v_mfma_f32_16x16x32_bf16 v[118:121], v[190:193], v[220:223], v[118:121]
	v_mfma_f32_16x16x32_bf16 v[114:117], v[212:215], v[220:223], v[114:117]
	v_mfma_f32_16x16x32_bf16 v[102:105], v[190:193], v[228:231], v[102:105]
	v_mfma_f32_16x16x32_bf16 v[98:101], v[212:215], v[228:231], v[98:101]
	v_mfma_f32_16x16x32_bf16 v[86:89], v[190:193], v[236:239], v[86:89]
	v_mfma_f32_16x16x32_bf16 v[82:85], v[212:215], v[236:239], v[82:85]
	v_mfma_f32_16x16x32_bf16 v[70:73], v[190:193], v[244:247], v[70:73]
	v_mfma_f32_16x16x32_bf16 v[66:69], v[212:215], v[244:247], v[66:69]
	s_barrier
	s_add_i32 s33, s33, s10
	v_lshl_add_u64 v[170:171], v[170:171], 0, s[70:71]
	s_mov_b32 m0, s33
	ds_read_b128 v[216:219], v165 offset:49152
	ds_read_b128 v[220:223], v165 offset:50176
	ds_read_b128 v[224:227], v165 offset:51200
	ds_read_b128 v[228:231], v165 offset:52224
	ds_read_b128 v[232:235], v165 offset:53248
	ds_read_b128 v[236:239], v165 offset:54272
	ds_read_b128 v[240:243], v165 offset:55296
	ds_read_b128 v[244:247], v165 offset:56320
	global_load_lds_dwordx4 v[170:171], off
	s_add_i32 m0, s33, 0x2000
	s_add_u32 s30, s30, 0xb0080
	v_lshl_add_u64 v[170:171], v[198:199], 0, s[70:71]
	s_addc_u32 s31, s31, 0
	s_add_i32 s33, s76, s10
	global_load_lds_dwordx4 v[170:171], off
	v_lshl_add_u64 v[170:171], s[30:31], 0, v[158:159]
	s_mov_b32 m0, s33
	s_nop 0
	global_load_lds_dwordx4 v[170:171], off
	v_lshl_add_u64 v[170:171], s[30:31], 0, v[162:163]
	s_add_i32 m0, s33, 0x2000
	s_nop 0
	global_load_lds_dwordx4 v[170:171], off
	v_lshl_add_u64 v[170:171], v[248:249], 0, s[70:71]
	s_mov_b32 m0, s55
	s_nop 0
	global_load_lds_dwordx4 v[170:171], off
	v_lshl_add_u64 v[170:171], v[250:251], 0, s[70:71]
	s_mov_b32 m0, s56
	s_nop 0
	global_load_lds_dwordx4 v[170:171], off
	s_waitcnt vmcnt(8)
	s_waitcnt lgkmcnt(0)
	s_barrier
	s_waitcnt lgkmcnt(0)
	v_mfma_f32_16x16x32_bf16 v[62:65], v[138:141], v[216:219], v[62:65]
	v_mfma_f32_16x16x32_bf16 v[58:61], v[174:177], v[216:219], v[58:61]
	v_mfma_f32_16x16x32_bf16 v[46:49], v[138:141], v[224:227], v[46:49]
	v_mfma_f32_16x16x32_bf16 v[42:45], v[174:177], v[224:227], v[42:45]
	v_mfma_f32_16x16x32_bf16 v[30:33], v[138:141], v[232:235], v[30:33]
	v_mfma_f32_16x16x32_bf16 v[26:29], v[174:177], v[232:235], v[26:29]
	v_mfma_f32_16x16x32_bf16 v[14:17], v[138:141], v[240:243], v[14:17]
	v_mfma_f32_16x16x32_bf16 v[10:13], v[174:177], v[240:243], v[10:13]
	v_mfma_f32_16x16x32_bf16 v[62:65], v[142:145], v[220:223], v[62:65]
	v_mfma_f32_16x16x32_bf16 v[58:61], v[182:185], v[220:223], v[58:61]
	v_mfma_f32_16x16x32_bf16 v[46:49], v[142:145], v[228:231], v[46:49]
	v_mfma_f32_16x16x32_bf16 v[42:45], v[182:185], v[228:231], v[42:45]
	v_mfma_f32_16x16x32_bf16 v[30:33], v[142:145], v[236:239], v[30:33]
	v_mfma_f32_16x16x32_bf16 v[26:29], v[182:185], v[236:239], v[26:29]
	v_mfma_f32_16x16x32_bf16 v[14:17], v[142:145], v[244:247], v[14:17]
	v_mfma_f32_16x16x32_bf16 v[10:13], v[182:185], v[244:247], v[10:13]
	v_mfma_f32_16x16x32_bf16 v[54:57], v[186:189], v[216:219], v[54:57]
	v_mfma_f32_16x16x32_bf16 v[50:53], v[194:197], v[216:219], v[50:53]
	v_mfma_f32_16x16x32_bf16 v[38:41], v[186:189], v[224:227], v[38:41]
	v_mfma_f32_16x16x32_bf16 v[34:37], v[194:197], v[224:227], v[34:37]
	v_mfma_f32_16x16x32_bf16 v[22:25], v[186:189], v[232:235], v[22:25]
	v_mfma_f32_16x16x32_bf16 v[18:21], v[194:197], v[232:235], v[18:21]
	v_mfma_f32_16x16x32_bf16 v[6:9], v[186:189], v[240:243], v[6:9]
	v_mfma_f32_16x16x32_bf16 v[2:5], v[194:197], v[240:243], v[2:5]
	v_mfma_f32_16x16x32_bf16 v[54:57], v[190:193], v[220:223], v[54:57]
	v_mfma_f32_16x16x32_bf16 v[50:53], v[212:215], v[220:223], v[50:53]
	v_mfma_f32_16x16x32_bf16 v[38:41], v[190:193], v[228:231], v[38:41]
	v_mfma_f32_16x16x32_bf16 v[34:37], v[212:215], v[228:231], v[34:37]
	v_mfma_f32_16x16x32_bf16 v[22:25], v[190:193], v[236:239], v[22:25]
	v_mfma_f32_16x16x32_bf16 v[18:21], v[212:215], v[236:239], v[18:21]
	v_mfma_f32_16x16x32_bf16 v[6:9], v[190:193], v[244:247], v[6:9]
	v_mfma_f32_16x16x32_bf16 v[2:5], v[212:215], v[244:247], v[2:5]
	s_barrier
	s_add_i32 s75, s75, 2
	s_add_u32 s8, s8, 0x100
	s_addc_u32 s9, s9, 0
	s_add_u32 s67, s67, 0x100
	s_addc_u32 s74, s74, 0
	s_cmp_gt_u32 s75, 41
	s_cbranch_scc0 .LBB0_446
	s_and_b64 vcc, exec, s[78:79]
	s_cbranch_vccz .LBB0_449
	s_barrier

.LBB0_617:
	ds_read_b128 v[138:141], v155
	ds_read_b128 v[174:177], v155 offset:1024
	ds_read_b128 v[182:185], v155 offset:2048
	ds_read_b128 v[186:189], v155 offset:3072
	ds_read_b128 v[190:193], v157
	ds_read_b128 v[194:197], v157 offset:1024
	ds_read_b128 v[212:215], v157 offset:2048
	ds_read_b128 v[216:219], v157 offset:3072
	s_add_u32 s30, s74, 0xfffc0080
	s_addc_u32 s31, s75, -1
	s_cmp_eq_u32 s92, 12
	s_cselect_b32 s73, s1, s31
	s_cselect_b32 s72, s6, s30
	s_cselect_b32 s31, s7, s87
	s_cselect_b32 s30, s9, s83
	v_lshl_add_u64 v[142:143], s[74:75], 0, v[132:133]
	s_add_i32 m0, s11, 0xc000
	ds_read_b128 v[220:223], v159
	ds_read_b128 v[224:227], v159 offset:1024
	ds_read_b128 v[228:231], v159 offset:2048
	ds_read_b128 v[232:235], v159 offset:3072
	ds_read_b128 v[236:239], v159 offset:4096
	ds_read_b128 v[240:243], v159 offset:5120
	ds_read_b128 v[244:247], v159 offset:6144
	ds_read_b128 v[248:251], v159 offset:7168
	global_load_lds_dwordx4 v[142:143], off
	v_lshl_add_u64 v[142:143], s[74:75], 0, v[134:135]
	s_add_i32 m0, s11, 0xe000
	s_nop 0
	global_load_lds_dwordx4 v[142:143], off
	s_waitcnt vmcnt(8)
	s_waitcnt lgkmcnt(0)
	s_barrier
	s_waitcnt lgkmcnt(0)
	v_mfma_f32_16x16x32_bf16 v[126:129], v[138:141], v[220:223], v[126:129]
	v_mfma_f32_16x16x32_bf16 v[122:125], v[182:185], v[220:223], v[122:125]
	v_mfma_f32_16x16x32_bf16 v[110:113], v[138:141], v[228:231], v[110:113]
	v_mfma_f32_16x16x32_bf16 v[106:109], v[182:185], v[228:231], v[106:109]
	v_mfma_f32_16x16x32_bf16 v[94:97], v[138:141], v[236:239], v[94:97]
	v_mfma_f32_16x16x32_bf16 v[90:93], v[182:185], v[236:239], v[90:93]
	v_mfma_f32_16x16x32_bf16 v[78:81], v[138:141], v[244:247], v[78:81]
	v_mfma_f32_16x16x32_bf16 v[74:77], v[182:185], v[244:247], v[74:77]
	v_mfma_f32_16x16x32_bf16 v[126:129], v[174:177], v[224:227], v[126:129]
	v_mfma_f32_16x16x32_bf16 v[122:125], v[186:189], v[224:227], v[122:125]
	v_mfma_f32_16x16x32_bf16 v[110:113], v[174:177], v[232:235], v[110:113]
	v_mfma_f32_16x16x32_bf16 v[106:109], v[186:189], v[232:235], v[106:109]
	v_mfma_f32_16x16x32_bf16 v[94:97], v[174:177], v[240:243], v[94:97]
	v_mfma_f32_16x16x32_bf16 v[90:93], v[186:189], v[240:243], v[90:93]
	v_mfma_f32_16x16x32_bf16 v[78:81], v[174:177], v[248:251], v[78:81]
	v_mfma_f32_16x16x32_bf16 v[74:77], v[186:189], v[248:251], v[74:77]
	v_mfma_f32_16x16x32_bf16 v[118:121], v[190:193], v[220:223], v[118:121]
	v_mfma_f32_16x16x32_bf16 v[114:117], v[212:215], v[220:223], v[114:117]
	v_mfma_f32_16x16x32_bf16 v[102:105], v[190:193], v[228:231], v[102:105]
	v_mfma_f32_16x16x32_bf16 v[98:101], v[212:215], v[228:231], v[98:101]
	v_mfma_f32_16x16x32_bf16 v[86:89], v[190:193], v[236:239], v[86:89]
	v_mfma_f32_16x16x32_bf16 v[82:85], v[212:215], v[236:239], v[82:85]
	v_mfma_f32_16x16x32_bf16 v[70:73], v[190:193], v[244:247], v[70:73]
	v_mfma_f32_16x16x32_bf16 v[66:69], v[212:215], v[244:247], v[66:69]
	v_mfma_f32_16x16x32_bf16 v[118:121], v[194:197], v[224:227], v[118:121]
	v_mfma_f32_16x16x32_bf16 v[114:117], v[216:219], v[224:227], v[114:117]
	v_mfma_f32_16x16x32_bf16 v[102:105], v[194:197], v[232:235], v[102:105]
	v_mfma_f32_16x16x32_bf16 v[98:101], v[216:219], v[232:235], v[98:101]
	v_mfma_f32_16x16x32_bf16 v[86:89], v[194:197], v[240:243], v[86:89]
	v_mfma_f32_16x16x32_bf16 v[82:85], v[216:219], v[240:243], v[82:85]
	v_mfma_f32_16x16x32_bf16 v[70:73], v[194:197], v[248:251], v[70:73]
	v_mfma_f32_16x16x32_bf16 v[66:69], v[216:219], v[248:251], v[66:69]
	s_barrier
	s_add_i32 s33, s66, s10
	v_lshl_add_u64 v[142:143], s[30:31], 0, v[148:149]
	s_mov_b32 m0, s33
	ds_read_b128 v[220:223], v159 offset:16384
	ds_read_b128 v[224:227], v159 offset:17408
	ds_read_b128 v[228:231], v159 offset:18432
	ds_read_b128 v[232:235], v159 offset:19456
	ds_read_b128 v[236:239], v159 offset:20480
	ds_read_b128 v[240:243], v159 offset:21504
	ds_read_b128 v[244:247], v159 offset:22528
	ds_read_b128 v[248:251], v159 offset:23552
	global_load_lds_dwordx4 v[142:143], off
	s_add_i32 m0, s33, 0x2000
	s_add_u32 s76, s30, 0x40000
	v_lshl_add_u64 v[170:171], s[30:31], 0, v[152:153]
	s_addc_u32 s77, s31, 0
	s_add_i32 s33, s67, s10
	global_load_lds_dwordx4 v[170:171], off
	v_lshl_add_u64 v[198:199], s[76:77], 0, v[148:149]
	s_mov_b32 m0, s33
	v_lshl_add_u64 v[252:253], s[72:73], 0, v[150:151]
	global_load_lds_dwordx4 v[198:199], off
	v_lshl_add_u64 v[198:199], s[76:77], 0, v[152:153]
	s_add_i32 m0, s33, 0x2000
	s_nop 0
	global_load_lds_dwordx4 v[198:199], off
	v_lshl_add_u64 v[198:199], s[72:73], 0, v[146:147]
	s_mov_b32 m0, s11
	s_nop 0
	global_load_lds_dwordx4 v[198:199], off
	s_mov_b32 m0, s35
	s_nop 0
	global_load_lds_dwordx4 v[252:253], off
	s_waitcnt vmcnt(8)
	s_waitcnt lgkmcnt(0)
	s_barrier
	s_waitcnt lgkmcnt(0)
	v_mfma_f32_16x16x32_bf16 v[62:65], v[138:141], v[220:223], v[62:65]
	v_mfma_f32_16x16x32_bf16 v[58:61], v[182:185], v[220:223], v[58:61]
	v_mfma_f32_16x16x32_bf16 v[46:49], v[138:141], v[228:231], v[46:49]
	v_mfma_f32_16x16x32_bf16 v[42:45], v[182:185], v[228:231], v[42:45]
	v_mfma_f32_16x16x32_bf16 v[30:33], v[138:141], v[236:239], v[30:33]
	v_mfma_f32_16x16x32_bf16 v[26:29], v[182:185], v[236:239], v[26:29]
	v_mfma_f32_16x16x32_bf16 v[14:17], v[138:141], v[244:247], v[14:17]
	v_mfma_f32_16x16x32_bf16 v[10:13], v[182:185], v[244:247], v[10:13]
	v_mfma_f32_16x16x32_bf16 v[62:65], v[174:177], v[224:227], v[62:65]
	v_mfma_f32_16x16x32_bf16 v[58:61], v[186:189], v[224:227], v[58:61]
	v_mfma_f32_16x16x32_bf16 v[46:49], v[174:177], v[232:235], v[46:49]
	v_mfma_f32_16x16x32_bf16 v[42:45], v[186:189], v[232:235], v[42:45]
	v_mfma_f32_16x16x32_bf16 v[30:33], v[174:177], v[240:243], v[30:33]
	v_mfma_f32_16x16x32_bf16 v[26:29], v[186:189], v[240:243], v[26:29]
	v_mfma_f32_16x16x32_bf16 v[14:17], v[174:177], v[248:251], v[14:17]
	v_mfma_f32_16x16x32_bf16 v[10:13], v[186:189], v[248:251], v[10:13]
	v_mfma_f32_16x16x32_bf16 v[54:57], v[190:193], v[220:223], v[54:57]
	v_mfma_f32_16x16x32_bf16 v[50:53], v[212:215], v[220:223], v[50:53]
	v_mfma_f32_16x16x32_bf16 v[38:41], v[190:193], v[228:231], v[38:41]
	v_mfma_f32_16x16x32_bf16 v[34:37], v[212:215], v[228:231], v[34:37]
	v_mfma_f32_16x16x32_bf16 v[22:25], v[190:193], v[236:239], v[22:25]
	v_mfma_f32_16x16x32_bf16 v[18:21], v[212:215], v[236:239], v[18:21]
	v_mfma_f32_16x16x32_bf16 v[6:9], v[190:193], v[244:247], v[6:9]
	v_mfma_f32_16x16x32_bf16 v[2:5], v[212:215], v[244:247], v[2:5]
	v_mfma_f32_16x16x32_bf16 v[54:57], v[194:197], v[224:227], v[54:57]
	v_mfma_f32_16x16x32_bf16 v[50:53], v[216:219], v[224:227], v[50:53]
	v_mfma_f32_16x16x32_bf16 v[38:41], v[194:197], v[232:235], v[38:41]
	v_mfma_f32_16x16x32_bf16 v[34:37], v[216:219], v[232:235], v[34:37]
	v_mfma_f32_16x16x32_bf16 v[22:25], v[194:197], v[240:243], v[22:25]
	v_mfma_f32_16x16x32_bf16 v[18:21], v[216:219], v[240:243], v[18:21]
	v_mfma_f32_16x16x32_bf16 v[6:9], v[194:197], v[248:251], v[6:9]
	v_mfma_f32_16x16x32_bf16 v[2:5], v[216:219], v[248:251], v[2:5]
	s_barrier
	s_add_i32 s33, 0, 0x18000
	v_add_u32_e32 v144, s33, v131
	s_add_i32 s76, 0, 0x1c000
	ds_read_b128 v[138:141], v144
	ds_read_b128 v[174:177], v144 offset:1024
	ds_read_b128 v[182:185], v144 offset:2048
	ds_read_b128 v[186:189], v144 offset:3072
	v_add_u32_e32 v144, s76, v131
	ds_read_b128 v[190:193], v144
	ds_read_b128 v[194:197], v144 offset:1024
	ds_read_b128 v[212:215], v144 offset:2048
	ds_read_b128 v[216:219], v144 offset:3072
	s_add_u32 s72, s72, 0x40000
	s_addc_u32 s73, s73, 0
	s_mov_b32 m0, s52
	v_lshl_add_u64 v[202:203], s[72:73], 0, v[146:147]
	ds_read_b128 v[220:223], v159 offset:32768
	ds_read_b128 v[224:227], v159 offset:33792
	ds_read_b128 v[228:231], v159 offset:34816
	ds_read_b128 v[232:235], v159 offset:35840
	ds_read_b128 v[236:239], v159 offset:36864
	ds_read_b128 v[240:243], v159 offset:37888
	ds_read_b128 v[244:247], v159 offset:38912
	ds_read_b128 v[248:251], v159 offset:39936
	global_load_lds_dwordx4 v[202:203], off
	v_lshl_add_u64 v[202:203], s[72:73], 0, v[150:151]
	s_mov_b32 m0, s53
	s_nop 0
	global_load_lds_dwordx4 v[202:203], off
	s_waitcnt vmcnt(8)
	s_waitcnt lgkmcnt(0)
	s_barrier
	s_waitcnt lgkmcnt(0)
	v_mfma_f32_16x16x32_bf16 v[126:129], v[138:141], v[220:223], v[126:129]
	v_mfma_f32_16x16x32_bf16 v[122:125], v[182:185], v[220:223], v[122:125]
	v_mfma_f32_16x16x32_bf16 v[110:113], v[138:141], v[228:231], v[110:113]
	v_mfma_f32_16x16x32_bf16 v[106:109], v[182:185], v[228:231], v[106:109]
	v_mfma_f32_16x16x32_bf16 v[94:97], v[138:141], v[236:239], v[94:97]
	v_mfma_f32_16x16x32_bf16 v[90:93], v[182:185], v[236:239], v[90:93]
	v_mfma_f32_16x16x32_bf16 v[78:81], v[138:141], v[244:247], v[78:81]
	v_mfma_f32_16x16x32_bf16 v[74:77], v[182:185], v[244:247], v[74:77]
	v_mfma_f32_16x16x32_bf16 v[126:129], v[174:177], v[224:227], v[126:129]
	v_mfma_f32_16x16x32_bf16 v[122:125], v[186:189], v[224:227], v[122:125]
	v_mfma_f32_16x16x32_bf16 v[110:113], v[174:177], v[232:235], v[110:113]
	v_mfma_f32_16x16x32_bf16 v[106:109], v[186:189], v[232:235], v[106:109]
	v_mfma_f32_16x16x32_bf16 v[94:97], v[174:177], v[240:243], v[94:97]
	v_mfma_f32_16x16x32_bf16 v[90:93], v[186:189], v[240:243], v[90:93]
	v_mfma_f32_16x16x32_bf16 v[78:81], v[174:177], v[248:251], v[78:81]
	v_mfma_f32_16x16x32_bf16 v[74:77], v[186:189], v[248:251], v[74:77]
	v_mfma_f32_16x16x32_bf16 v[118:121], v[190:193], v[220:223], v[118:121]
	v_mfma_f32_16x16x32_bf16 v[114:117], v[212:215], v[220:223], v[114:117]
	v_mfma_f32_16x16x32_bf16 v[102:105], v[190:193], v[228:231], v[102:105]
	v_mfma_f32_16x16x32_bf16 v[98:101], v[212:215], v[228:231], v[98:101]
	v_mfma_f32_16x16x32_bf16 v[86:89], v[190:193], v[236:239], v[86:89]
	v_mfma_f32_16x16x32_bf16 v[82:85], v[212:215], v[236:239], v[82:85]
	v_mfma_f32_16x16x32_bf16 v[70:73], v[190:193], v[244:247], v[70:73]
	v_mfma_f32_16x16x32_bf16 v[66:69], v[212:215], v[244:247], v[66:69]
	v_mfma_f32_16x16x32_bf16 v[118:121], v[194:197], v[224:227], v[118:121]
	v_mfma_f32_16x16x32_bf16 v[114:117], v[216:219], v[224:227], v[114:117]
	v_mfma_f32_16x16x32_bf16 v[102:105], v[194:197], v[232:235], v[102:105]
	v_mfma_f32_16x16x32_bf16 v[98:101], v[216:219], v[232:235], v[98:101]
	v_mfma_f32_16x16x32_bf16 v[86:89], v[194:197], v[240:243], v[86:89]
	v_mfma_f32_16x16x32_bf16 v[82:85], v[216:219], v[240:243], v[82:85]
	v_mfma_f32_16x16x32_bf16 v[70:73], v[194:197], v[248:251], v[70:73]
	v_mfma_f32_16x16x32_bf16 v[66:69], v[216:219], v[248:251], v[66:69]
	s_barrier
	s_add_i32 s33, s33, s10
	v_lshl_add_u64 v[142:143], v[142:143], 0, s[60:61]
	s_mov_b32 m0, s33
	ds_read_b128 v[220:223], v159 offset:49152
	ds_read_b128 v[224:227], v159 offset:50176
	ds_read_b128 v[228:231], v159 offset:51200
	ds_read_b128 v[232:235], v159 offset:52224
	ds_read_b128 v[236:239], v159 offset:53248
	ds_read_b128 v[240:243], v159 offset:54272
	ds_read_b128 v[244:247], v159 offset:55296
	ds_read_b128 v[248:251], v159 offset:56320
	global_load_lds_dwordx4 v[142:143], off
	s_add_i32 m0, s33, 0x2000
	s_add_u32 s30, s30, 0x40080
	v_lshl_add_u64 v[142:143], v[170:171], 0, s[60:61]
	s_addc_u32 s31, s31, 0
	s_add_i32 s33, s76, s10
	global_load_lds_dwordx4 v[142:143], off
	v_lshl_add_u64 v[142:143], s[30:31], 0, v[148:149]
	s_mov_b32 m0, s33
	s_nop 0
	global_load_lds_dwordx4 v[142:143], off
	v_lshl_add_u64 v[142:143], s[30:31], 0, v[152:153]
	s_add_i32 m0, s33, 0x2000
	s_nop 0
	global_load_lds_dwordx4 v[142:143], off
	v_lshl_add_u64 v[142:143], v[198:199], 0, s[60:61]
	s_mov_b32 m0, s56
	s_nop 0
	global_load_lds_dwordx4 v[142:143], off
	v_lshl_add_u64 v[142:143], v[252:253], 0, s[60:61]
	s_mov_b32 m0, s57
	s_nop 0
	global_load_lds_dwordx4 v[142:143], off
	s_waitcnt vmcnt(8)
	s_waitcnt lgkmcnt(0)
	s_barrier
	s_waitcnt lgkmcnt(0)
	v_mfma_f32_16x16x32_bf16 v[62:65], v[138:141], v[220:223], v[62:65]
	v_mfma_f32_16x16x32_bf16 v[58:61], v[182:185], v[220:223], v[58:61]
	v_mfma_f32_16x16x32_bf16 v[46:49], v[138:141], v[228:231], v[46:49]
	v_mfma_f32_16x16x32_bf16 v[42:45], v[182:185], v[228:231], v[42:45]
	v_mfma_f32_16x16x32_bf16 v[30:33], v[138:141], v[236:239], v[30:33]
	v_mfma_f32_16x16x32_bf16 v[26:29], v[182:185], v[236:239], v[26:29]
	v_mfma_f32_16x16x32_bf16 v[14:17], v[138:141], v[244:247], v[14:17]
	v_mfma_f32_16x16x32_bf16 v[10:13], v[182:185], v[244:247], v[10:13]
	v_mfma_f32_16x16x32_bf16 v[62:65], v[174:177], v[224:227], v[62:65]
	v_mfma_f32_16x16x32_bf16 v[58:61], v[186:189], v[224:227], v[58:61]
	v_mfma_f32_16x16x32_bf16 v[46:49], v[174:177], v[232:235], v[46:49]
	v_mfma_f32_16x16x32_bf16 v[42:45], v[186:189], v[232:235], v[42:45]
	v_mfma_f32_16x16x32_bf16 v[30:33], v[174:177], v[240:243], v[30:33]
	v_mfma_f32_16x16x32_bf16 v[26:29], v[186:189], v[240:243], v[26:29]
	v_mfma_f32_16x16x32_bf16 v[14:17], v[174:177], v[248:251], v[14:17]
	v_mfma_f32_16x16x32_bf16 v[10:13], v[186:189], v[248:251], v[10:13]
	v_mfma_f32_16x16x32_bf16 v[54:57], v[190:193], v[220:223], v[54:57]
	v_mfma_f32_16x16x32_bf16 v[50:53], v[212:215], v[220:223], v[50:53]
	v_mfma_f32_16x16x32_bf16 v[38:41], v[190:193], v[228:231], v[38:41]
	v_mfma_f32_16x16x32_bf16 v[34:37], v[212:215], v[228:231], v[34:37]
	v_mfma_f32_16x16x32_bf16 v[22:25], v[190:193], v[236:239], v[22:25]
	v_mfma_f32_16x16x32_bf16 v[18:21], v[212:215], v[236:239], v[18:21]
	v_mfma_f32_16x16x32_bf16 v[6:9], v[190:193], v[244:247], v[6:9]
	v_mfma_f32_16x16x32_bf16 v[2:5], v[212:215], v[244:247], v[2:5]
	v_mfma_f32_16x16x32_bf16 v[54:57], v[194:197], v[224:227], v[54:57]
	v_mfma_f32_16x16x32_bf16 v[50:53], v[216:219], v[224:227], v[50:53]
	v_mfma_f32_16x16x32_bf16 v[38:41], v[194:197], v[232:235], v[38:41]
	v_mfma_f32_16x16x32_bf16 v[34:37], v[216:219], v[232:235], v[34:37]
	v_mfma_f32_16x16x32_bf16 v[22:25], v[194:197], v[240:243], v[22:25]
	v_mfma_f32_16x16x32_bf16 v[18:21], v[216:219], v[240:243], v[18:21]
	v_mfma_f32_16x16x32_bf16 v[6:9], v[194:197], v[248:251], v[6:9]
	v_mfma_f32_16x16x32_bf16 v[2:5], v[216:219], v[248:251], v[2:5]
	s_barrier
	s_add_i32 s92, s92, 2
	s_add_u32 s74, s74, 0x100
	s_addc_u32 s75, s75, 0
	s_add_u32 s83, s83, 0x100
	s_addc_u32 s87, s87, 0
	s_cmp_gt_u32 s92, 13
	s_cbranch_scc0 .LBB0_617
	s_and_b64 vcc, exec, s[68:69]
	s_cbranch_vccz .LBB0_620
	s_barrier

.LBB0_1384:
	ds_read_b128 v[138:141], v165
	ds_read_b128 v[142:145], v165 offset:1024
	ds_read_b128 v[174:177], v165 offset:2048
	ds_read_b128 v[180:183], v165 offset:3072
	ds_read_b128 v[184:187], v168
	ds_read_b128 v[188:191], v168 offset:1024
	ds_read_b128 v[192:195], v168 offset:2048
	ds_read_b128 v[196:199], v168 offset:3072
	s_add_u32 s30, s76, 0xfffc0080
	s_addc_u32 s31, s77, -1
	s_cmp_eq_u32 s91, 12
	s_cselect_b32 s79, s6, s31
	s_cselect_b32 s78, s7, s30
	s_cselect_b32 s31, s9, s90
	s_cselect_b32 s30, s65, s69
	v_lshl_add_u64 v[166:167], s[76:77], 0, v[130:131]
	s_add_i32 m0, s11, 0xc000
	ds_read_b128 v[212:215], v171
	ds_read_b128 v[216:219], v171 offset:1024
	ds_read_b128 v[220:223], v171 offset:2048
	ds_read_b128 v[224:227], v171 offset:3072
	ds_read_b128 v[228:231], v171 offset:4096
	ds_read_b128 v[232:235], v171 offset:5120
	ds_read_b128 v[236:239], v171 offset:6144
	ds_read_b128 v[240:243], v171 offset:7168
	global_load_lds_dwordx4 v[166:167], off
	v_lshl_add_u64 v[166:167], s[76:77], 0, v[132:133]
	s_add_i32 m0, s11, 0xe000
	s_nop 0
	global_load_lds_dwordx4 v[166:167], off
	s_waitcnt vmcnt(8)
	s_waitcnt lgkmcnt(0)
	s_barrier
	s_waitcnt lgkmcnt(0)
	v_mfma_f32_16x16x32_bf16 v[126:129], v[138:141], v[212:215], v[126:129]
	v_mfma_f32_16x16x32_bf16 v[122:125], v[174:177], v[212:215], v[122:125]
	v_mfma_f32_16x16x32_bf16 v[110:113], v[138:141], v[220:223], v[110:113]
	v_mfma_f32_16x16x32_bf16 v[106:109], v[174:177], v[220:223], v[106:109]
	v_mfma_f32_16x16x32_bf16 v[94:97], v[138:141], v[228:231], v[94:97]
	v_mfma_f32_16x16x32_bf16 v[90:93], v[174:177], v[228:231], v[90:93]
	v_mfma_f32_16x16x32_bf16 v[78:81], v[138:141], v[236:239], v[78:81]
	v_mfma_f32_16x16x32_bf16 v[74:77], v[174:177], v[236:239], v[74:77]
	v_mfma_f32_16x16x32_bf16 v[126:129], v[142:145], v[216:219], v[126:129]
	v_mfma_f32_16x16x32_bf16 v[122:125], v[180:183], v[216:219], v[122:125]
	v_mfma_f32_16x16x32_bf16 v[110:113], v[142:145], v[224:227], v[110:113]
	v_mfma_f32_16x16x32_bf16 v[106:109], v[180:183], v[224:227], v[106:109]
	v_mfma_f32_16x16x32_bf16 v[94:97], v[142:145], v[232:235], v[94:97]
	v_mfma_f32_16x16x32_bf16 v[90:93], v[180:183], v[232:235], v[90:93]
	v_mfma_f32_16x16x32_bf16 v[78:81], v[142:145], v[240:243], v[78:81]
	v_mfma_f32_16x16x32_bf16 v[74:77], v[180:183], v[240:243], v[74:77]
	v_mfma_f32_16x16x32_bf16 v[118:121], v[184:187], v[212:215], v[118:121]
	v_mfma_f32_16x16x32_bf16 v[114:117], v[192:195], v[212:215], v[114:117]
	v_mfma_f32_16x16x32_bf16 v[102:105], v[184:187], v[220:223], v[102:105]
	v_mfma_f32_16x16x32_bf16 v[98:101], v[192:195], v[220:223], v[98:101]
	v_mfma_f32_16x16x32_bf16 v[86:89], v[184:187], v[228:231], v[86:89]
	v_mfma_f32_16x16x32_bf16 v[82:85], v[192:195], v[228:231], v[82:85]
	v_mfma_f32_16x16x32_bf16 v[70:73], v[184:187], v[236:239], v[70:73]
	v_mfma_f32_16x16x32_bf16 v[66:69], v[192:195], v[236:239], v[66:69]
	v_mfma_f32_16x16x32_bf16 v[118:121], v[188:191], v[216:219], v[118:121]
	v_mfma_f32_16x16x32_bf16 v[114:117], v[196:199], v[216:219], v[114:117]
	v_mfma_f32_16x16x32_bf16 v[102:105], v[188:191], v[224:227], v[102:105]
	v_mfma_f32_16x16x32_bf16 v[98:101], v[196:199], v[224:227], v[98:101]
	v_mfma_f32_16x16x32_bf16 v[86:89], v[188:191], v[232:235], v[86:89]
	v_mfma_f32_16x16x32_bf16 v[82:85], v[196:199], v[232:235], v[82:85]
	v_mfma_f32_16x16x32_bf16 v[70:73], v[188:191], v[240:243], v[70:73]
	v_mfma_f32_16x16x32_bf16 v[66:69], v[196:199], v[240:243], v[66:69]
	s_barrier
	s_add_i32 s33, s88, s10
	v_lshl_add_u64 v[166:167], s[30:31], 0, v[148:149]
	s_mov_b32 m0, s33
	ds_read_b128 v[212:215], v171 offset:16384
	ds_read_b128 v[216:219], v171 offset:17408
	ds_read_b128 v[220:223], v171 offset:18432
	ds_read_b128 v[224:227], v171 offset:19456
	ds_read_b128 v[228:231], v171 offset:20480
	ds_read_b128 v[232:235], v171 offset:21504
	ds_read_b128 v[236:239], v171 offset:22528
	ds_read_b128 v[240:243], v171 offset:23552
	global_load_lds_dwordx4 v[166:167], off
	s_add_i32 m0, s33, 0x2000
	s_add_u32 s92, s30, 0x40000
	v_lshl_add_u64 v[202:203], s[30:31], 0, v[152:153]
	s_addc_u32 s93, s31, 0
	s_add_i32 s33, s89, s10
	global_load_lds_dwordx4 v[202:203], off
	v_lshl_add_u64 v[244:245], s[92:93], 0, v[148:149]
	s_mov_b32 m0, s33
	v_lshl_add_u64 v[246:247], s[78:79], 0, v[150:151]
	global_load_lds_dwordx4 v[244:245], off
	v_lshl_add_u64 v[244:245], s[92:93], 0, v[152:153]
	s_add_i32 m0, s33, 0x2000
	s_nop 0
	global_load_lds_dwordx4 v[244:245], off
	v_lshl_add_u64 v[244:245], s[78:79], 0, v[146:147]
	s_mov_b32 m0, s11
	s_nop 0
	global_load_lds_dwordx4 v[244:245], off
	s_mov_b32 m0, s66
	s_nop 0
	global_load_lds_dwordx4 v[246:247], off
	s_waitcnt vmcnt(8)
	s_waitcnt lgkmcnt(0)
	s_barrier
	s_waitcnt lgkmcnt(0)
	v_mfma_f32_16x16x32_bf16 v[62:65], v[138:141], v[212:215], v[62:65]
	v_mfma_f32_16x16x32_bf16 v[58:61], v[174:177], v[212:215], v[58:61]
	v_mfma_f32_16x16x32_bf16 v[46:49], v[138:141], v[220:223], v[46:49]
	v_mfma_f32_16x16x32_bf16 v[42:45], v[174:177], v[220:223], v[42:45]
	v_mfma_f32_16x16x32_bf16 v[30:33], v[138:141], v[228:231], v[30:33]
	v_mfma_f32_16x16x32_bf16 v[26:29], v[174:177], v[228:231], v[26:29]
	v_mfma_f32_16x16x32_bf16 v[14:17], v[138:141], v[236:239], v[14:17]
	v_mfma_f32_16x16x32_bf16 v[10:13], v[174:177], v[236:239], v[10:13]
	v_mfma_f32_16x16x32_bf16 v[62:65], v[142:145], v[216:219], v[62:65]
	v_mfma_f32_16x16x32_bf16 v[58:61], v[180:183], v[216:219], v[58:61]
	v_mfma_f32_16x16x32_bf16 v[46:49], v[142:145], v[224:227], v[46:49]
	v_mfma_f32_16x16x32_bf16 v[42:45], v[180:183], v[224:227], v[42:45]
	v_mfma_f32_16x16x32_bf16 v[30:33], v[142:145], v[232:235], v[30:33]
	v_mfma_f32_16x16x32_bf16 v[26:29], v[180:183], v[232:235], v[26:29]
	v_mfma_f32_16x16x32_bf16 v[14:17], v[142:145], v[240:243], v[14:17]
	v_mfma_f32_16x16x32_bf16 v[10:13], v[180:183], v[240:243], v[10:13]
	v_mfma_f32_16x16x32_bf16 v[54:57], v[184:187], v[212:215], v[54:57]
	v_mfma_f32_16x16x32_bf16 v[50:53], v[192:195], v[212:215], v[50:53]
	v_mfma_f32_16x16x32_bf16 v[38:41], v[184:187], v[220:223], v[38:41]
	v_mfma_f32_16x16x32_bf16 v[34:37], v[192:195], v[220:223], v[34:37]
	v_mfma_f32_16x16x32_bf16 v[22:25], v[184:187], v[228:231], v[22:25]
	v_mfma_f32_16x16x32_bf16 v[18:21], v[192:195], v[228:231], v[18:21]
	v_mfma_f32_16x16x32_bf16 v[6:9], v[184:187], v[236:239], v[6:9]
	v_mfma_f32_16x16x32_bf16 v[2:5], v[192:195], v[236:239], v[2:5]
	v_mfma_f32_16x16x32_bf16 v[54:57], v[188:191], v[216:219], v[54:57]
	v_mfma_f32_16x16x32_bf16 v[50:53], v[196:199], v[216:219], v[50:53]
	v_mfma_f32_16x16x32_bf16 v[38:41], v[188:191], v[224:227], v[38:41]
	v_mfma_f32_16x16x32_bf16 v[34:37], v[196:199], v[224:227], v[34:37]
	v_mfma_f32_16x16x32_bf16 v[22:25], v[188:191], v[232:235], v[22:25]
	v_mfma_f32_16x16x32_bf16 v[18:21], v[196:199], v[232:235], v[18:21]
	v_mfma_f32_16x16x32_bf16 v[6:9], v[188:191], v[240:243], v[6:9]
	v_mfma_f32_16x16x32_bf16 v[2:5], v[196:199], v[240:243], v[2:5]
	s_barrier
	s_add_i32 s33, 0, 0x18000
	v_add_u32_e32 v172, s33, v161
	s_add_i32 s92, 0, 0x1c000
	ds_read_b128 v[138:141], v172
	ds_read_b128 v[142:145], v172 offset:1024
	ds_read_b128 v[174:177], v172 offset:2048
	ds_read_b128 v[180:183], v172 offset:3072
	v_add_u32_e32 v172, s92, v161
	ds_read_b128 v[184:187], v172
	ds_read_b128 v[188:191], v172 offset:1024
	ds_read_b128 v[192:195], v172 offset:2048
	ds_read_b128 v[196:199], v172 offset:3072
	s_add_u32 s78, s78, 0x40000
	s_addc_u32 s79, s79, 0
	s_mov_b32 m0, s67
	v_lshl_add_u64 v[248:249], s[78:79], 0, v[146:147]
	ds_read_b128 v[212:215], v171 offset:32768
	ds_read_b128 v[216:219], v171 offset:33792
	ds_read_b128 v[220:223], v171 offset:34816
	ds_read_b128 v[224:227], v171 offset:35840
	ds_read_b128 v[228:231], v171 offset:36864
	ds_read_b128 v[232:235], v171 offset:37888
	ds_read_b128 v[236:239], v171 offset:38912
	ds_read_b128 v[240:243], v171 offset:39936
	global_load_lds_dwordx4 v[248:249], off
	v_lshl_add_u64 v[248:249], s[78:79], 0, v[150:151]
	s_mov_b32 m0, s75
	s_nop 0
	global_load_lds_dwordx4 v[248:249], off
	s_waitcnt vmcnt(8)
	s_waitcnt lgkmcnt(0)
	s_barrier
	s_waitcnt lgkmcnt(0)
	v_mfma_f32_16x16x32_bf16 v[126:129], v[138:141], v[212:215], v[126:129]
	v_mfma_f32_16x16x32_bf16 v[122:125], v[174:177], v[212:215], v[122:125]
	v_mfma_f32_16x16x32_bf16 v[110:113], v[138:141], v[220:223], v[110:113]
	v_mfma_f32_16x16x32_bf16 v[106:109], v[174:177], v[220:223], v[106:109]
	v_mfma_f32_16x16x32_bf16 v[94:97], v[138:141], v[228:231], v[94:97]
	v_mfma_f32_16x16x32_bf16 v[90:93], v[174:177], v[228:231], v[90:93]
	v_mfma_f32_16x16x32_bf16 v[78:81], v[138:141], v[236:239], v[78:81]
	v_mfma_f32_16x16x32_bf16 v[74:77], v[174:177], v[236:239], v[74:77]
	v_mfma_f32_16x16x32_bf16 v[126:129], v[142:145], v[216:219], v[126:129]
	v_mfma_f32_16x16x32_bf16 v[122:125], v[180:183], v[216:219], v[122:125]
	v_mfma_f32_16x16x32_bf16 v[110:113], v[142:145], v[224:227], v[110:113]
	v_mfma_f32_16x16x32_bf16 v[106:109], v[180:183], v[224:227], v[106:109]
	v_mfma_f32_16x16x32_bf16 v[94:97], v[142:145], v[232:235], v[94:97]
	v_mfma_f32_16x16x32_bf16 v[90:93], v[180:183], v[232:235], v[90:93]
	v_mfma_f32_16x16x32_bf16 v[78:81], v[142:145], v[240:243], v[78:81]
	v_mfma_f32_16x16x32_bf16 v[74:77], v[180:183], v[240:243], v[74:77]
	v_mfma_f32_16x16x32_bf16 v[118:121], v[184:187], v[212:215], v[118:121]
	v_mfma_f32_16x16x32_bf16 v[114:117], v[192:195], v[212:215], v[114:117]
	v_mfma_f32_16x16x32_bf16 v[102:105], v[184:187], v[220:223], v[102:105]
	v_mfma_f32_16x16x32_bf16 v[98:101], v[192:195], v[220:223], v[98:101]
	v_mfma_f32_16x16x32_bf16 v[86:89], v[184:187], v[228:231], v[86:89]
	v_mfma_f32_16x16x32_bf16 v[82:85], v[192:195], v[228:231], v[82:85]
	v_mfma_f32_16x16x32_bf16 v[70:73], v[184:187], v[236:239], v[70:73]
	v_mfma_f32_16x16x32_bf16 v[66:69], v[192:195], v[236:239], v[66:69]
	v_mfma_f32_16x16x32_bf16 v[118:121], v[188:191], v[216:219], v[118:121]
	v_mfma_f32_16x16x32_bf16 v[114:117], v[196:199], v[216:219], v[114:117]
	v_mfma_f32_16x16x32_bf16 v[102:105], v[188:191], v[224:227], v[102:105]
	v_mfma_f32_16x16x32_bf16 v[98:101], v[196:199], v[224:227], v[98:101]
	v_mfma_f32_16x16x32_bf16 v[86:89], v[188:191], v[232:235], v[86:89]
	v_mfma_f32_16x16x32_bf16 v[82:85], v[196:199], v[232:235], v[82:85]
	v_mfma_f32_16x16x32_bf16 v[70:73], v[188:191], v[240:243], v[70:73]
	v_mfma_f32_16x16x32_bf16 v[66:69], v[196:199], v[240:243], v[66:69]
	s_barrier
	s_add_i32 s33, s33, s10
	v_lshl_add_u64 v[166:167], v[166:167], 0, s[20:21]
	s_mov_b32 m0, s33
	ds_read_b128 v[212:215], v171 offset:49152
	ds_read_b128 v[216:219], v171 offset:50176
	ds_read_b128 v[220:223], v171 offset:51200
	ds_read_b128 v[224:227], v171 offset:52224
	ds_read_b128 v[228:231], v171 offset:53248
	ds_read_b128 v[232:235], v171 offset:54272
	ds_read_b128 v[236:239], v171 offset:55296
	ds_read_b128 v[240:243], v171 offset:56320
	global_load_lds_dwordx4 v[166:167], off
	s_add_i32 m0, s33, 0x2000
	s_add_u32 s30, s30, 0x40080
	v_lshl_add_u64 v[166:167], v[202:203], 0, s[20:21]
	s_addc_u32 s31, s31, 0
	s_add_i32 s33, s92, s10
	global_load_lds_dwordx4 v[166:167], off
	v_lshl_add_u64 v[166:167], s[30:31], 0, v[148:149]
	s_mov_b32 m0, s33
	s_nop 0
	global_load_lds_dwordx4 v[166:167], off
	v_lshl_add_u64 v[166:167], s[30:31], 0, v[152:153]
	s_add_i32 m0, s33, 0x2000
	s_nop 0
	global_load_lds_dwordx4 v[166:167], off
	v_lshl_add_u64 v[166:167], v[244:245], 0, s[20:21]
	s_mov_b32 m0, s85
	s_nop 0
	global_load_lds_dwordx4 v[166:167], off
	v_lshl_add_u64 v[166:167], v[246:247], 0, s[20:21]
	s_mov_b32 m0, s86
	s_nop 0
	global_load_lds_dwordx4 v[166:167], off
	s_waitcnt vmcnt(8)
	s_waitcnt lgkmcnt(0)
	s_barrier
	s_waitcnt lgkmcnt(0)
	v_mfma_f32_16x16x32_bf16 v[62:65], v[138:141], v[212:215], v[62:65]
	v_mfma_f32_16x16x32_bf16 v[58:61], v[174:177], v[212:215], v[58:61]
	v_mfma_f32_16x16x32_bf16 v[46:49], v[138:141], v[220:223], v[46:49]
	v_mfma_f32_16x16x32_bf16 v[42:45], v[174:177], v[220:223], v[42:45]
	v_mfma_f32_16x16x32_bf16 v[30:33], v[138:141], v[228:231], v[30:33]
	v_mfma_f32_16x16x32_bf16 v[26:29], v[174:177], v[228:231], v[26:29]
	v_mfma_f32_16x16x32_bf16 v[14:17], v[138:141], v[236:239], v[14:17]
	v_mfma_f32_16x16x32_bf16 v[10:13], v[174:177], v[236:239], v[10:13]
	v_mfma_f32_16x16x32_bf16 v[62:65], v[142:145], v[216:219], v[62:65]
	v_mfma_f32_16x16x32_bf16 v[58:61], v[180:183], v[216:219], v[58:61]
	v_mfma_f32_16x16x32_bf16 v[46:49], v[142:145], v[224:227], v[46:49]
	v_mfma_f32_16x16x32_bf16 v[42:45], v[180:183], v[224:227], v[42:45]
	v_mfma_f32_16x16x32_bf16 v[30:33], v[142:145], v[232:235], v[30:33]
	v_mfma_f32_16x16x32_bf16 v[26:29], v[180:183], v[232:235], v[26:29]
	v_mfma_f32_16x16x32_bf16 v[14:17], v[142:145], v[240:243], v[14:17]
	v_mfma_f32_16x16x32_bf16 v[10:13], v[180:183], v[240:243], v[10:13]
	v_mfma_f32_16x16x32_bf16 v[54:57], v[184:187], v[212:215], v[54:57]
	v_mfma_f32_16x16x32_bf16 v[50:53], v[192:195], v[212:215], v[50:53]
	v_mfma_f32_16x16x32_bf16 v[38:41], v[184:187], v[220:223], v[38:41]
	v_mfma_f32_16x16x32_bf16 v[34:37], v[192:195], v[220:223], v[34:37]
	v_mfma_f32_16x16x32_bf16 v[22:25], v[184:187], v[228:231], v[22:25]
	v_mfma_f32_16x16x32_bf16 v[18:21], v[192:195], v[228:231], v[18:21]
	v_mfma_f32_16x16x32_bf16 v[6:9], v[184:187], v[236:239], v[6:9]
	v_mfma_f32_16x16x32_bf16 v[2:5], v[192:195], v[236:239], v[2:5]
	v_mfma_f32_16x16x32_bf16 v[54:57], v[188:191], v[216:219], v[54:57]
	v_mfma_f32_16x16x32_bf16 v[50:53], v[196:199], v[216:219], v[50:53]
	v_mfma_f32_16x16x32_bf16 v[38:41], v[188:191], v[224:227], v[38:41]
	v_mfma_f32_16x16x32_bf16 v[34:37], v[196:199], v[224:227], v[34:37]
	v_mfma_f32_16x16x32_bf16 v[22:25], v[188:191], v[232:235], v[22:25]
	v_mfma_f32_16x16x32_bf16 v[18:21], v[196:199], v[232:235], v[18:21]
	v_mfma_f32_16x16x32_bf16 v[6:9], v[188:191], v[240:243], v[6:9]
	v_mfma_f32_16x16x32_bf16 v[2:5], v[196:199], v[240:243], v[2:5]
	s_barrier
	s_add_i32 s91, s91, 2
	s_add_u32 s76, s76, 0x100
	s_addc_u32 s77, s77, 0
	s_add_u32 s69, s69, 0x100
	s_addc_u32 s90, s90, 0
	s_cmp_gt_u32 s91, 13
	s_cbranch_scc0 .LBB0_1384
	s_and_b64 vcc, exec, s[22:23]
	s_cbranch_vccz .LBB0_1387
	s_barrier

.LBB0_1524:
	ds_read_b128 v[138:141], v159
	ds_read_b128 v[174:177], v159 offset:1024
	ds_read_b128 v[180:183], v159 offset:2048
	ds_read_b128 v[184:187], v159 offset:3072
	ds_read_b128 v[188:191], v161
	ds_read_b128 v[192:195], v161 offset:1024
	ds_read_b128 v[196:199], v161 offset:2048
	ds_read_b128 v[212:215], v161 offset:3072
	s_add_u32 s30, s4, 0xfffc0080
	s_addc_u32 s31, s5, -1
	s_cmp_eq_u32 s79, 12
	s_cselect_b32 s65, s6, s31
	s_cselect_b32 s64, s7, s30
	s_cselect_b32 s31, s25, s78
	s_cselect_b32 s30, s59, s77
	v_lshl_add_u64 v[142:143], s[4:5], 0, v[130:131]
	s_add_i32 m0, s11, 0xc000
	ds_read_b128 v[216:219], v163
	ds_read_b128 v[220:223], v163 offset:1024
	ds_read_b128 v[224:227], v163 offset:2048
	ds_read_b128 v[228:231], v163 offset:3072
	ds_read_b128 v[232:235], v163 offset:4096
	ds_read_b128 v[236:239], v163 offset:5120
	ds_read_b128 v[240:243], v163 offset:6144
	ds_read_b128 v[244:247], v163 offset:7168
	global_load_lds_dwordx4 v[142:143], off
	v_lshl_add_u64 v[142:143], s[4:5], 0, v[132:133]
	s_add_i32 m0, s11, 0xe000
	s_nop 0
	global_load_lds_dwordx4 v[142:143], off
	s_waitcnt vmcnt(8)
	s_waitcnt lgkmcnt(0)
	s_barrier
	s_waitcnt lgkmcnt(0)
	v_mfma_f32_16x16x32_bf16 v[126:129], v[138:141], v[216:219], v[126:129]
	v_mfma_f32_16x16x32_bf16 v[122:125], v[180:183], v[216:219], v[122:125]
	v_mfma_f32_16x16x32_bf16 v[110:113], v[138:141], v[224:227], v[110:113]
	v_mfma_f32_16x16x32_bf16 v[106:109], v[180:183], v[224:227], v[106:109]
	v_mfma_f32_16x16x32_bf16 v[94:97], v[138:141], v[232:235], v[94:97]
	v_mfma_f32_16x16x32_bf16 v[90:93], v[180:183], v[232:235], v[90:93]
	v_mfma_f32_16x16x32_bf16 v[78:81], v[138:141], v[240:243], v[78:81]
	v_mfma_f32_16x16x32_bf16 v[74:77], v[180:183], v[240:243], v[74:77]
	v_mfma_f32_16x16x32_bf16 v[126:129], v[174:177], v[220:223], v[126:129]
	v_mfma_f32_16x16x32_bf16 v[122:125], v[184:187], v[220:223], v[122:125]
	v_mfma_f32_16x16x32_bf16 v[110:113], v[174:177], v[228:231], v[110:113]
	v_mfma_f32_16x16x32_bf16 v[106:109], v[184:187], v[228:231], v[106:109]
	v_mfma_f32_16x16x32_bf16 v[94:97], v[174:177], v[236:239], v[94:97]
	v_mfma_f32_16x16x32_bf16 v[90:93], v[184:187], v[236:239], v[90:93]
	v_mfma_f32_16x16x32_bf16 v[78:81], v[174:177], v[244:247], v[78:81]
	v_mfma_f32_16x16x32_bf16 v[74:77], v[184:187], v[244:247], v[74:77]
	v_mfma_f32_16x16x32_bf16 v[118:121], v[188:191], v[216:219], v[118:121]
	v_mfma_f32_16x16x32_bf16 v[114:117], v[196:199], v[216:219], v[114:117]
	v_mfma_f32_16x16x32_bf16 v[102:105], v[188:191], v[224:227], v[102:105]
	v_mfma_f32_16x16x32_bf16 v[98:101], v[196:199], v[224:227], v[98:101]
	v_mfma_f32_16x16x32_bf16 v[86:89], v[188:191], v[232:235], v[86:89]
	v_mfma_f32_16x16x32_bf16 v[82:85], v[196:199], v[232:235], v[82:85]
	v_mfma_f32_16x16x32_bf16 v[70:73], v[188:191], v[240:243], v[70:73]
	v_mfma_f32_16x16x32_bf16 v[66:69], v[196:199], v[240:243], v[66:69]
	v_mfma_f32_16x16x32_bf16 v[118:121], v[192:195], v[220:223], v[118:121]
	v_mfma_f32_16x16x32_bf16 v[114:117], v[212:215], v[220:223], v[114:117]
	v_mfma_f32_16x16x32_bf16 v[102:105], v[192:195], v[228:231], v[102:105]
	v_mfma_f32_16x16x32_bf16 v[98:101], v[212:215], v[228:231], v[98:101]
	v_mfma_f32_16x16x32_bf16 v[86:89], v[192:195], v[236:239], v[86:89]
	v_mfma_f32_16x16x32_bf16 v[82:85], v[212:215], v[236:239], v[82:85]
	v_mfma_f32_16x16x32_bf16 v[70:73], v[192:195], v[244:247], v[70:73]
	v_mfma_f32_16x16x32_bf16 v[66:69], v[212:215], v[244:247], v[66:69]
	s_barrier
	s_add_i32 s33, s72, s10
	v_lshl_add_u64 v[142:143], s[30:31], 0, v[148:149]
	s_mov_b32 m0, s33
	ds_read_b128 v[216:219], v163 offset:16384
	ds_read_b128 v[220:223], v163 offset:17408
	ds_read_b128 v[224:227], v163 offset:18432
	ds_read_b128 v[228:231], v163 offset:19456
	ds_read_b128 v[232:235], v163 offset:20480
	ds_read_b128 v[236:239], v163 offset:21504
	ds_read_b128 v[240:243], v163 offset:22528
	ds_read_b128 v[244:247], v163 offset:23552
	global_load_lds_dwordx4 v[142:143], off
	s_add_i32 m0, s33, 0x2000
	s_add_u32 s82, s30, 0x40000
	v_lshl_add_u64 v[166:167], s[30:31], 0, v[152:153]
	s_addc_u32 s83, s31, 0
	s_add_i32 s33, s73, s10
	global_load_lds_dwordx4 v[166:167], off
	v_lshl_add_u64 v[202:203], s[82:83], 0, v[148:149]
	s_mov_b32 m0, s33
	v_lshl_add_u64 v[248:249], s[64:65], 0, v[150:151]
	global_load_lds_dwordx4 v[202:203], off
	v_lshl_add_u64 v[202:203], s[82:83], 0, v[152:153]
	s_add_i32 m0, s33, 0x2000
	s_nop 0
	global_load_lds_dwordx4 v[202:203], off
	v_lshl_add_u64 v[202:203], s[64:65], 0, v[146:147]
	s_mov_b32 m0, s11
	s_nop 0
	global_load_lds_dwordx4 v[202:203], off
	s_mov_b32 m0, s66
	s_nop 0
	global_load_lds_dwordx4 v[248:249], off
	s_waitcnt vmcnt(8)
	s_waitcnt lgkmcnt(0)
	s_barrier
	s_waitcnt lgkmcnt(0)
	v_mfma_f32_16x16x32_bf16 v[62:65], v[138:141], v[216:219], v[62:65]
	v_mfma_f32_16x16x32_bf16 v[58:61], v[180:183], v[216:219], v[58:61]
	v_mfma_f32_16x16x32_bf16 v[46:49], v[138:141], v[224:227], v[46:49]
	v_mfma_f32_16x16x32_bf16 v[42:45], v[180:183], v[224:227], v[42:45]
	v_mfma_f32_16x16x32_bf16 v[30:33], v[138:141], v[232:235], v[30:33]
	v_mfma_f32_16x16x32_bf16 v[26:29], v[180:183], v[232:235], v[26:29]
	v_mfma_f32_16x16x32_bf16 v[14:17], v[138:141], v[240:243], v[14:17]
	v_mfma_f32_16x16x32_bf16 v[10:13], v[180:183], v[240:243], v[10:13]
	v_mfma_f32_16x16x32_bf16 v[62:65], v[174:177], v[220:223], v[62:65]
	v_mfma_f32_16x16x32_bf16 v[58:61], v[184:187], v[220:223], v[58:61]
	v_mfma_f32_16x16x32_bf16 v[46:49], v[174:177], v[228:231], v[46:49]
	v_mfma_f32_16x16x32_bf16 v[42:45], v[184:187], v[228:231], v[42:45]
	v_mfma_f32_16x16x32_bf16 v[30:33], v[174:177], v[236:239], v[30:33]
	v_mfma_f32_16x16x32_bf16 v[26:29], v[184:187], v[236:239], v[26:29]
	v_mfma_f32_16x16x32_bf16 v[14:17], v[174:177], v[244:247], v[14:17]
	v_mfma_f32_16x16x32_bf16 v[10:13], v[184:187], v[244:247], v[10:13]
	v_mfma_f32_16x16x32_bf16 v[54:57], v[188:191], v[216:219], v[54:57]
	v_mfma_f32_16x16x32_bf16 v[50:53], v[196:199], v[216:219], v[50:53]
	v_mfma_f32_16x16x32_bf16 v[38:41], v[188:191], v[224:227], v[38:41]
	v_mfma_f32_16x16x32_bf16 v[34:37], v[196:199], v[224:227], v[34:37]
	v_mfma_f32_16x16x32_bf16 v[22:25], v[188:191], v[232:235], v[22:25]
	v_mfma_f32_16x16x32_bf16 v[18:21], v[196:199], v[232:235], v[18:21]
	v_mfma_f32_16x16x32_bf16 v[6:9], v[188:191], v[240:243], v[6:9]
	v_mfma_f32_16x16x32_bf16 v[2:5], v[196:199], v[240:243], v[2:5]
	v_mfma_f32_16x16x32_bf16 v[54:57], v[192:195], v[220:223], v[54:57]
	v_mfma_f32_16x16x32_bf16 v[50:53], v[212:215], v[220:223], v[50:53]
	v_mfma_f32_16x16x32_bf16 v[38:41], v[192:195], v[228:231], v[38:41]
	v_mfma_f32_16x16x32_bf16 v[34:37], v[212:215], v[228:231], v[34:37]
	v_mfma_f32_16x16x32_bf16 v[22:25], v[192:195], v[236:239], v[22:25]
	v_mfma_f32_16x16x32_bf16 v[18:21], v[212:215], v[236:239], v[18:21]
	v_mfma_f32_16x16x32_bf16 v[6:9], v[192:195], v[244:247], v[6:9]
	v_mfma_f32_16x16x32_bf16 v[2:5], v[212:215], v[244:247], v[2:5]
	s_barrier
	s_add_i32 s33, 0, 0x18000
	v_add_u32_e32 v168, s33, v145
	s_add_i32 s81, 0, 0x1c000
	ds_read_b128 v[138:141], v168
	ds_read_b128 v[174:177], v168 offset:1024
	ds_read_b128 v[180:183], v168 offset:2048
	ds_read_b128 v[184:187], v168 offset:3072
	v_add_u32_e32 v168, s81, v145
	ds_read_b128 v[188:191], v168
	ds_read_b128 v[192:195], v168 offset:1024
	ds_read_b128 v[196:199], v168 offset:2048
	ds_read_b128 v[212:215], v168 offset:3072
	s_add_u32 s64, s64, 0x40000
	s_addc_u32 s65, s65, 0
	s_mov_b32 m0, s67
	v_lshl_add_u64 v[250:251], s[64:65], 0, v[146:147]
	ds_read_b128 v[216:219], v163 offset:32768
	ds_read_b128 v[220:223], v163 offset:33792
	ds_read_b128 v[224:227], v163 offset:34816
	ds_read_b128 v[228:231], v163 offset:35840
	ds_read_b128 v[232:235], v163 offset:36864
	ds_read_b128 v[236:239], v163 offset:37888
	ds_read_b128 v[240:243], v163 offset:38912
	ds_read_b128 v[244:247], v163 offset:39936
	global_load_lds_dwordx4 v[250:251], off
	v_lshl_add_u64 v[250:251], s[64:65], 0, v[150:151]
	s_mov_b32 m0, s68
	s_nop 0
	global_load_lds_dwordx4 v[250:251], off
	s_waitcnt vmcnt(8)
	s_waitcnt lgkmcnt(0)
	s_barrier
	s_waitcnt lgkmcnt(0)
	v_mfma_f32_16x16x32_bf16 v[126:129], v[138:141], v[216:219], v[126:129]
	v_mfma_f32_16x16x32_bf16 v[122:125], v[180:183], v[216:219], v[122:125]
	v_mfma_f32_16x16x32_bf16 v[110:113], v[138:141], v[224:227], v[110:113]
	v_mfma_f32_16x16x32_bf16 v[106:109], v[180:183], v[224:227], v[106:109]
	v_mfma_f32_16x16x32_bf16 v[94:97], v[138:141], v[232:235], v[94:97]
	v_mfma_f32_16x16x32_bf16 v[90:93], v[180:183], v[232:235], v[90:93]
	v_mfma_f32_16x16x32_bf16 v[78:81], v[138:141], v[240:243], v[78:81]
	v_mfma_f32_16x16x32_bf16 v[74:77], v[180:183], v[240:243], v[74:77]
	v_mfma_f32_16x16x32_bf16 v[126:129], v[174:177], v[220:223], v[126:129]
	v_mfma_f32_16x16x32_bf16 v[122:125], v[184:187], v[220:223], v[122:125]
	v_mfma_f32_16x16x32_bf16 v[110:113], v[174:177], v[228:231], v[110:113]
	v_mfma_f32_16x16x32_bf16 v[106:109], v[184:187], v[228:231], v[106:109]
	v_mfma_f32_16x16x32_bf16 v[94:97], v[174:177], v[236:239], v[94:97]
	v_mfma_f32_16x16x32_bf16 v[90:93], v[184:187], v[236:239], v[90:93]
	v_mfma_f32_16x16x32_bf16 v[78:81], v[174:177], v[244:247], v[78:81]
	v_mfma_f32_16x16x32_bf16 v[74:77], v[184:187], v[244:247], v[74:77]
	v_mfma_f32_16x16x32_bf16 v[118:121], v[188:191], v[216:219], v[118:121]
	v_mfma_f32_16x16x32_bf16 v[114:117], v[196:199], v[216:219], v[114:117]
	v_mfma_f32_16x16x32_bf16 v[102:105], v[188:191], v[224:227], v[102:105]
	v_mfma_f32_16x16x32_bf16 v[98:101], v[196:199], v[224:227], v[98:101]
	v_mfma_f32_16x16x32_bf16 v[86:89], v[188:191], v[232:235], v[86:89]
	v_mfma_f32_16x16x32_bf16 v[82:85], v[196:199], v[232:235], v[82:85]
	v_mfma_f32_16x16x32_bf16 v[70:73], v[188:191], v[240:243], v[70:73]
	v_mfma_f32_16x16x32_bf16 v[66:69], v[196:199], v[240:243], v[66:69]
	v_mfma_f32_16x16x32_bf16 v[118:121], v[192:195], v[220:223], v[118:121]
	v_mfma_f32_16x16x32_bf16 v[114:117], v[212:215], v[220:223], v[114:117]
	v_mfma_f32_16x16x32_bf16 v[102:105], v[192:195], v[228:231], v[102:105]
	v_mfma_f32_16x16x32_bf16 v[98:101], v[212:215], v[228:231], v[98:101]
	v_mfma_f32_16x16x32_bf16 v[86:89], v[192:195], v[236:239], v[86:89]
	v_mfma_f32_16x16x32_bf16 v[82:85], v[212:215], v[236:239], v[82:85]
	v_mfma_f32_16x16x32_bf16 v[70:73], v[192:195], v[244:247], v[70:73]
	v_mfma_f32_16x16x32_bf16 v[66:69], v[212:215], v[244:247], v[66:69]
	s_barrier
	s_add_i32 s33, s33, s10
	v_lshl_add_u64 v[142:143], v[142:143], 0, s[20:21]
	s_mov_b32 m0, s33
	ds_read_b128 v[216:219], v163 offset:49152
	ds_read_b128 v[220:223], v163 offset:50176
	ds_read_b128 v[224:227], v163 offset:51200
	ds_read_b128 v[228:231], v163 offset:52224
	ds_read_b128 v[232:235], v163 offset:53248
	ds_read_b128 v[236:239], v163 offset:54272
	ds_read_b128 v[240:243], v163 offset:55296
	ds_read_b128 v[244:247], v163 offset:56320
	global_load_lds_dwordx4 v[142:143], off
	s_add_i32 m0, s33, 0x2000
	s_add_u32 s30, s30, 0x40080
	v_lshl_add_u64 v[142:143], v[166:167], 0, s[20:21]
	s_addc_u32 s31, s31, 0
	s_add_i32 s33, s81, s10
	global_load_lds_dwordx4 v[142:143], off
	v_lshl_add_u64 v[142:143], s[30:31], 0, v[148:149]
	s_mov_b32 m0, s33
	s_nop 0
	global_load_lds_dwordx4 v[142:143], off
	v_lshl_add_u64 v[142:143], s[30:31], 0, v[152:153]
	s_add_i32 m0, s33, 0x2000
	s_nop 0
	global_load_lds_dwordx4 v[142:143], off
	v_lshl_add_u64 v[142:143], v[202:203], 0, s[20:21]
	s_mov_b32 m0, s69
	s_nop 0
	global_load_lds_dwordx4 v[142:143], off
	v_lshl_add_u64 v[142:143], v[248:249], 0, s[20:21]
	s_mov_b32 m0, s70
	s_nop 0
	global_load_lds_dwordx4 v[142:143], off
	s_waitcnt vmcnt(8)
	s_waitcnt lgkmcnt(0)
	s_barrier
	s_waitcnt lgkmcnt(0)
	v_mfma_f32_16x16x32_bf16 v[62:65], v[138:141], v[216:219], v[62:65]
	v_mfma_f32_16x16x32_bf16 v[58:61], v[180:183], v[216:219], v[58:61]
	v_mfma_f32_16x16x32_bf16 v[46:49], v[138:141], v[224:227], v[46:49]
	v_mfma_f32_16x16x32_bf16 v[42:45], v[180:183], v[224:227], v[42:45]
	v_mfma_f32_16x16x32_bf16 v[30:33], v[138:141], v[232:235], v[30:33]
	v_mfma_f32_16x16x32_bf16 v[26:29], v[180:183], v[232:235], v[26:29]
	v_mfma_f32_16x16x32_bf16 v[14:17], v[138:141], v[240:243], v[14:17]
	v_mfma_f32_16x16x32_bf16 v[10:13], v[180:183], v[240:243], v[10:13]
	v_mfma_f32_16x16x32_bf16 v[62:65], v[174:177], v[220:223], v[62:65]
	v_mfma_f32_16x16x32_bf16 v[58:61], v[184:187], v[220:223], v[58:61]
	v_mfma_f32_16x16x32_bf16 v[46:49], v[174:177], v[228:231], v[46:49]
	v_mfma_f32_16x16x32_bf16 v[42:45], v[184:187], v[228:231], v[42:45]
	v_mfma_f32_16x16x32_bf16 v[30:33], v[174:177], v[236:239], v[30:33]
	v_mfma_f32_16x16x32_bf16 v[26:29], v[184:187], v[236:239], v[26:29]
	v_mfma_f32_16x16x32_bf16 v[14:17], v[174:177], v[244:247], v[14:17]
	v_mfma_f32_16x16x32_bf16 v[10:13], v[184:187], v[244:247], v[10:13]
	v_mfma_f32_16x16x32_bf16 v[54:57], v[188:191], v[216:219], v[54:57]
	v_mfma_f32_16x16x32_bf16 v[50:53], v[196:199], v[216:219], v[50:53]
	v_mfma_f32_16x16x32_bf16 v[38:41], v[188:191], v[224:227], v[38:41]
	v_mfma_f32_16x16x32_bf16 v[34:37], v[196:199], v[224:227], v[34:37]
	v_mfma_f32_16x16x32_bf16 v[22:25], v[188:191], v[232:235], v[22:25]
	v_mfma_f32_16x16x32_bf16 v[18:21], v[196:199], v[232:235], v[18:21]
	v_mfma_f32_16x16x32_bf16 v[6:9], v[188:191], v[240:243], v[6:9]
	v_mfma_f32_16x16x32_bf16 v[2:5], v[196:199], v[240:243], v[2:5]
	v_mfma_f32_16x16x32_bf16 v[54:57], v[192:195], v[220:223], v[54:57]
	v_mfma_f32_16x16x32_bf16 v[50:53], v[212:215], v[220:223], v[50:53]
	v_mfma_f32_16x16x32_bf16 v[38:41], v[192:195], v[228:231], v[38:41]
	v_mfma_f32_16x16x32_bf16 v[34:37], v[212:215], v[228:231], v[34:37]
	v_mfma_f32_16x16x32_bf16 v[22:25], v[192:195], v[236:239], v[22:25]
	v_mfma_f32_16x16x32_bf16 v[18:21], v[212:215], v[236:239], v[18:21]
	v_mfma_f32_16x16x32_bf16 v[6:9], v[192:195], v[244:247], v[6:9]
	v_mfma_f32_16x16x32_bf16 v[2:5], v[212:215], v[244:247], v[2:5]
	s_barrier
	s_add_i32 s79, s79, 2
	s_add_u32 s4, s4, 0x100
	s_addc_u32 s5, s5, 0
	s_add_u32 s77, s77, 0x100
	s_addc_u32 s78, s78, 0
	s_cmp_gt_u32 s79, 13
	s_cbranch_scc0 .LBB0_1524
	s_and_b64 vcc, exec, s[22:23]
	s_cbranch_vccz .LBB0_1527
	s_barrier

.LBB0_1649:
	ds_read_b128 v[138:141], v163
	ds_read_b128 v[142:145], v163 offset:1024
	ds_read_b128 v[174:177], v163 offset:2048
	ds_read_b128 v[180:183], v163 offset:3072
	ds_read_b128 v[184:187], v166
	ds_read_b128 v[188:191], v166 offset:1024
	ds_read_b128 v[192:195], v166 offset:2048
	ds_read_b128 v[196:199], v166 offset:3072
	s_add_u32 s30, s54, 0xfffc0080
	s_addc_u32 s31, s55, -1
	s_cmp_eq_u32 s73, 12
	s_cselect_b32 s59, s6, s31
	s_cselect_b32 s58, s7, s30
	s_cselect_b32 s31, s9, s72
	s_cselect_b32 s30, s45, s71
	v_lshl_add_u64 v[164:165], s[54:55], 0, v[130:131]
	s_add_i32 m0, s11, 0xc000
	ds_read_b128 v[210:213], v167
	ds_read_b128 v[214:217], v167 offset:1024
	ds_read_b128 v[218:221], v167 offset:2048
	ds_read_b128 v[222:225], v167 offset:3072
	ds_read_b128 v[226:229], v167 offset:4096
	ds_read_b128 v[230:233], v167 offset:5120
	ds_read_b128 v[234:237], v167 offset:6144
	ds_read_b128 v[238:241], v167 offset:7168
	global_load_lds_dwordx4 v[164:165], off
	v_lshl_add_u64 v[164:165], s[54:55], 0, v[132:133]
	s_add_i32 m0, s11, 0xe000
	s_nop 0
	global_load_lds_dwordx4 v[164:165], off
	s_waitcnt vmcnt(8)
	s_waitcnt lgkmcnt(0)
	s_barrier
	s_waitcnt lgkmcnt(0)
	v_mfma_f32_16x16x32_bf16 v[126:129], v[138:141], v[210:213], v[126:129]
	v_mfma_f32_16x16x32_bf16 v[122:125], v[174:177], v[210:213], v[122:125]
	v_mfma_f32_16x16x32_bf16 v[110:113], v[138:141], v[218:221], v[110:113]
	v_mfma_f32_16x16x32_bf16 v[106:109], v[174:177], v[218:221], v[106:109]
	v_mfma_f32_16x16x32_bf16 v[94:97], v[138:141], v[226:229], v[94:97]
	v_mfma_f32_16x16x32_bf16 v[90:93], v[174:177], v[226:229], v[90:93]
	v_mfma_f32_16x16x32_bf16 v[78:81], v[138:141], v[234:237], v[78:81]
	v_mfma_f32_16x16x32_bf16 v[74:77], v[174:177], v[234:237], v[74:77]
	v_mfma_f32_16x16x32_bf16 v[126:129], v[142:145], v[214:217], v[126:129]
	v_mfma_f32_16x16x32_bf16 v[122:125], v[180:183], v[214:217], v[122:125]
	v_mfma_f32_16x16x32_bf16 v[110:113], v[142:145], v[222:225], v[110:113]
	v_mfma_f32_16x16x32_bf16 v[106:109], v[180:183], v[222:225], v[106:109]
	v_mfma_f32_16x16x32_bf16 v[94:97], v[142:145], v[230:233], v[94:97]
	v_mfma_f32_16x16x32_bf16 v[90:93], v[180:183], v[230:233], v[90:93]
	v_mfma_f32_16x16x32_bf16 v[78:81], v[142:145], v[238:241], v[78:81]
	v_mfma_f32_16x16x32_bf16 v[74:77], v[180:183], v[238:241], v[74:77]
	v_mfma_f32_16x16x32_bf16 v[118:121], v[184:187], v[210:213], v[118:121]
	v_mfma_f32_16x16x32_bf16 v[114:117], v[192:195], v[210:213], v[114:117]
	v_mfma_f32_16x16x32_bf16 v[102:105], v[184:187], v[218:221], v[102:105]
	v_mfma_f32_16x16x32_bf16 v[98:101], v[192:195], v[218:221], v[98:101]
	v_mfma_f32_16x16x32_bf16 v[86:89], v[184:187], v[226:229], v[86:89]
	v_mfma_f32_16x16x32_bf16 v[82:85], v[192:195], v[226:229], v[82:85]
	v_mfma_f32_16x16x32_bf16 v[70:73], v[184:187], v[234:237], v[70:73]
	v_mfma_f32_16x16x32_bf16 v[66:69], v[192:195], v[234:237], v[66:69]
	v_mfma_f32_16x16x32_bf16 v[118:121], v[188:191], v[214:217], v[118:121]
	v_mfma_f32_16x16x32_bf16 v[114:117], v[196:199], v[214:217], v[114:117]
	v_mfma_f32_16x16x32_bf16 v[102:105], v[188:191], v[222:225], v[102:105]
	v_mfma_f32_16x16x32_bf16 v[98:101], v[196:199], v[222:225], v[98:101]
	v_mfma_f32_16x16x32_bf16 v[86:89], v[188:191], v[230:233], v[86:89]
	v_mfma_f32_16x16x32_bf16 v[82:85], v[196:199], v[230:233], v[82:85]
	v_mfma_f32_16x16x32_bf16 v[70:73], v[188:191], v[238:241], v[70:73]
	v_mfma_f32_16x16x32_bf16 v[66:69], v[196:199], v[238:241], v[66:69]
	s_barrier
	s_add_i32 s33, s67, s10
	v_lshl_add_u64 v[164:165], s[30:31], 0, v[148:149]
	s_mov_b32 m0, s33
	ds_read_b128 v[210:213], v167 offset:16384
	ds_read_b128 v[214:217], v167 offset:17408
	ds_read_b128 v[218:221], v167 offset:18432
	ds_read_b128 v[222:225], v167 offset:19456
	ds_read_b128 v[226:229], v167 offset:20480
	ds_read_b128 v[230:233], v167 offset:21504
	ds_read_b128 v[234:237], v167 offset:22528
	ds_read_b128 v[238:241], v167 offset:23552
	global_load_lds_dwordx4 v[164:165], off
	s_add_i32 m0, s33, 0x2000
	s_add_u32 s74, s30, 0x40000
	v_lshl_add_u64 v[170:171], s[30:31], 0, v[152:153]
	s_addc_u32 s75, s31, 0
	s_add_i32 s33, s68, s10
	global_load_lds_dwordx4 v[170:171], off
	v_lshl_add_u64 v[202:203], s[74:75], 0, v[148:149]
	s_mov_b32 m0, s33
	v_lshl_add_u64 v[242:243], s[58:59], 0, v[150:151]
	global_load_lds_dwordx4 v[202:203], off
	v_lshl_add_u64 v[202:203], s[74:75], 0, v[152:153]
	s_add_i32 m0, s33, 0x2000
	s_nop 0
	global_load_lds_dwordx4 v[202:203], off
	v_lshl_add_u64 v[202:203], s[58:59], 0, v[146:147]
	s_mov_b32 m0, s11
	s_nop 0
	global_load_lds_dwordx4 v[202:203], off
	s_mov_b32 m0, s53
	s_nop 0
	global_load_lds_dwordx4 v[242:243], off
	s_waitcnt vmcnt(8)
	s_waitcnt lgkmcnt(0)
	s_barrier
	s_waitcnt lgkmcnt(0)
	v_mfma_f32_16x16x32_bf16 v[62:65], v[138:141], v[210:213], v[62:65]
	v_mfma_f32_16x16x32_bf16 v[58:61], v[174:177], v[210:213], v[58:61]
	v_mfma_f32_16x16x32_bf16 v[46:49], v[138:141], v[218:221], v[46:49]
	v_mfma_f32_16x16x32_bf16 v[42:45], v[174:177], v[218:221], v[42:45]
	v_mfma_f32_16x16x32_bf16 v[30:33], v[138:141], v[226:229], v[30:33]
	v_mfma_f32_16x16x32_bf16 v[26:29], v[174:177], v[226:229], v[26:29]
	v_mfma_f32_16x16x32_bf16 v[14:17], v[138:141], v[234:237], v[14:17]
	v_mfma_f32_16x16x32_bf16 v[10:13], v[174:177], v[234:237], v[10:13]
	v_mfma_f32_16x16x32_bf16 v[62:65], v[142:145], v[214:217], v[62:65]
	v_mfma_f32_16x16x32_bf16 v[58:61], v[180:183], v[214:217], v[58:61]
	v_mfma_f32_16x16x32_bf16 v[46:49], v[142:145], v[222:225], v[46:49]
	v_mfma_f32_16x16x32_bf16 v[42:45], v[180:183], v[222:225], v[42:45]
	v_mfma_f32_16x16x32_bf16 v[30:33], v[142:145], v[230:233], v[30:33]
	v_mfma_f32_16x16x32_bf16 v[26:29], v[180:183], v[230:233], v[26:29]
	v_mfma_f32_16x16x32_bf16 v[14:17], v[142:145], v[238:241], v[14:17]
	v_mfma_f32_16x16x32_bf16 v[10:13], v[180:183], v[238:241], v[10:13]
	v_mfma_f32_16x16x32_bf16 v[54:57], v[184:187], v[210:213], v[54:57]
	v_mfma_f32_16x16x32_bf16 v[50:53], v[192:195], v[210:213], v[50:53]
	v_mfma_f32_16x16x32_bf16 v[38:41], v[184:187], v[218:221], v[38:41]
	v_mfma_f32_16x16x32_bf16 v[34:37], v[192:195], v[218:221], v[34:37]
	v_mfma_f32_16x16x32_bf16 v[22:25], v[184:187], v[226:229], v[22:25]
	v_mfma_f32_16x16x32_bf16 v[18:21], v[192:195], v[226:229], v[18:21]
	v_mfma_f32_16x16x32_bf16 v[6:9], v[184:187], v[234:237], v[6:9]
	v_mfma_f32_16x16x32_bf16 v[2:5], v[192:195], v[234:237], v[2:5]
	v_mfma_f32_16x16x32_bf16 v[54:57], v[188:191], v[214:217], v[54:57]
	v_mfma_f32_16x16x32_bf16 v[50:53], v[196:199], v[214:217], v[50:53]
	v_mfma_f32_16x16x32_bf16 v[38:41], v[188:191], v[222:225], v[38:41]
	v_mfma_f32_16x16x32_bf16 v[34:37], v[196:199], v[222:225], v[34:37]
	v_mfma_f32_16x16x32_bf16 v[22:25], v[188:191], v[230:233], v[22:25]
	v_mfma_f32_16x16x32_bf16 v[18:21], v[196:199], v[230:233], v[18:21]
	v_mfma_f32_16x16x32_bf16 v[6:9], v[188:191], v[238:241], v[6:9]
	v_mfma_f32_16x16x32_bf16 v[2:5], v[196:199], v[238:241], v[2:5]
	s_barrier
	s_add_i32 s33, 0, 0x18000
	v_add_u32_e32 v172, s33, v159
	s_add_i32 s74, 0, 0x1c000
	ds_read_b128 v[138:141], v172
	ds_read_b128 v[142:145], v172 offset:1024
	ds_read_b128 v[174:177], v172 offset:2048
	ds_read_b128 v[180:183], v172 offset:3072
	v_add_u32_e32 v172, s74, v159
	ds_read_b128 v[184:187], v172
	ds_read_b128 v[188:191], v172 offset:1024
	ds_read_b128 v[192:195], v172 offset:2048
	ds_read_b128 v[196:199], v172 offset:3072
	s_add_u32 s58, s58, 0x40000
	s_addc_u32 s59, s59, 0
	s_mov_b32 m0, s60
	v_lshl_add_u64 v[244:245], s[58:59], 0, v[146:147]
	ds_read_b128 v[210:213], v167 offset:32768
	ds_read_b128 v[214:217], v167 offset:33792
	ds_read_b128 v[218:221], v167 offset:34816
	ds_read_b128 v[222:225], v167 offset:35840
	ds_read_b128 v[226:229], v167 offset:36864
	ds_read_b128 v[230:233], v167 offset:37888
	ds_read_b128 v[234:237], v167 offset:38912
	ds_read_b128 v[238:241], v167 offset:39936
	global_load_lds_dwordx4 v[244:245], off
	v_lshl_add_u64 v[244:245], s[58:59], 0, v[150:151]
	s_mov_b32 m0, s61
	s_nop 0
	global_load_lds_dwordx4 v[244:245], off
	s_waitcnt vmcnt(8)
	s_waitcnt lgkmcnt(0)
	s_barrier
	s_waitcnt lgkmcnt(0)
	v_mfma_f32_16x16x32_bf16 v[126:129], v[138:141], v[210:213], v[126:129]
	v_mfma_f32_16x16x32_bf16 v[122:125], v[174:177], v[210:213], v[122:125]
	v_mfma_f32_16x16x32_bf16 v[110:113], v[138:141], v[218:221], v[110:113]
	v_mfma_f32_16x16x32_bf16 v[106:109], v[174:177], v[218:221], v[106:109]
	v_mfma_f32_16x16x32_bf16 v[94:97], v[138:141], v[226:229], v[94:97]
	v_mfma_f32_16x16x32_bf16 v[90:93], v[174:177], v[226:229], v[90:93]
	v_mfma_f32_16x16x32_bf16 v[78:81], v[138:141], v[234:237], v[78:81]
	v_mfma_f32_16x16x32_bf16 v[74:77], v[174:177], v[234:237], v[74:77]
	v_mfma_f32_16x16x32_bf16 v[126:129], v[142:145], v[214:217], v[126:129]
	v_mfma_f32_16x16x32_bf16 v[122:125], v[180:183], v[214:217], v[122:125]
	v_mfma_f32_16x16x32_bf16 v[110:113], v[142:145], v[222:225], v[110:113]
	v_mfma_f32_16x16x32_bf16 v[106:109], v[180:183], v[222:225], v[106:109]
	v_mfma_f32_16x16x32_bf16 v[94:97], v[142:145], v[230:233], v[94:97]
	v_mfma_f32_16x16x32_bf16 v[90:93], v[180:183], v[230:233], v[90:93]
	v_mfma_f32_16x16x32_bf16 v[78:81], v[142:145], v[238:241], v[78:81]
	v_mfma_f32_16x16x32_bf16 v[74:77], v[180:183], v[238:241], v[74:77]
	v_mfma_f32_16x16x32_bf16 v[118:121], v[184:187], v[210:213], v[118:121]
	v_mfma_f32_16x16x32_bf16 v[114:117], v[192:195], v[210:213], v[114:117]
	v_mfma_f32_16x16x32_bf16 v[102:105], v[184:187], v[218:221], v[102:105]
	v_mfma_f32_16x16x32_bf16 v[98:101], v[192:195], v[218:221], v[98:101]
	v_mfma_f32_16x16x32_bf16 v[86:89], v[184:187], v[226:229], v[86:89]
	v_mfma_f32_16x16x32_bf16 v[82:85], v[192:195], v[226:229], v[82:85]
	v_mfma_f32_16x16x32_bf16 v[70:73], v[184:187], v[234:237], v[70:73]
	v_mfma_f32_16x16x32_bf16 v[66:69], v[192:195], v[234:237], v[66:69]
	v_mfma_f32_16x16x32_bf16 v[118:121], v[188:191], v[214:217], v[118:121]
	v_mfma_f32_16x16x32_bf16 v[114:117], v[196:199], v[214:217], v[114:117]
	v_mfma_f32_16x16x32_bf16 v[102:105], v[188:191], v[222:225], v[102:105]
	v_mfma_f32_16x16x32_bf16 v[98:101], v[196:199], v[222:225], v[98:101]
	v_mfma_f32_16x16x32_bf16 v[86:89], v[188:191], v[230:233], v[86:89]
	v_mfma_f32_16x16x32_bf16 v[82:85], v[196:199], v[230:233], v[82:85]
	v_mfma_f32_16x16x32_bf16 v[70:73], v[188:191], v[238:241], v[70:73]
	v_mfma_f32_16x16x32_bf16 v[66:69], v[196:199], v[238:241], v[66:69]
	s_barrier
	s_add_i32 s33, s33, s10
	v_lshl_add_u64 v[164:165], v[164:165], 0, s[18:19]
	s_mov_b32 m0, s33
	ds_read_b128 v[210:213], v167 offset:49152
	ds_read_b128 v[214:217], v167 offset:50176
	ds_read_b128 v[218:221], v167 offset:51200
	ds_read_b128 v[222:225], v167 offset:52224
	ds_read_b128 v[226:229], v167 offset:53248
	ds_read_b128 v[230:233], v167 offset:54272
	ds_read_b128 v[234:237], v167 offset:55296
	ds_read_b128 v[238:241], v167 offset:56320
	global_load_lds_dwordx4 v[164:165], off
	s_add_i32 m0, s33, 0x2000
	s_add_u32 s30, s30, 0x40080
	v_lshl_add_u64 v[164:165], v[170:171], 0, s[18:19]
	s_addc_u32 s31, s31, 0
	s_add_i32 s33, s74, s10
	global_load_lds_dwordx4 v[164:165], off
	v_lshl_add_u64 v[164:165], s[30:31], 0, v[148:149]
	s_mov_b32 m0, s33
	s_nop 0
	global_load_lds_dwordx4 v[164:165], off
	v_lshl_add_u64 v[164:165], s[30:31], 0, v[152:153]
	s_add_i32 m0, s33, 0x2000
	s_nop 0
	global_load_lds_dwordx4 v[164:165], off
	v_lshl_add_u64 v[164:165], v[202:203], 0, s[18:19]
	s_mov_b32 m0, s63
	s_nop 0
	global_load_lds_dwordx4 v[164:165], off
	v_lshl_add_u64 v[164:165], v[242:243], 0, s[18:19]
	s_mov_b32 m0, s64
	s_nop 0
	global_load_lds_dwordx4 v[164:165], off
	s_waitcnt vmcnt(8)
	s_waitcnt lgkmcnt(0)
	s_barrier
	s_waitcnt lgkmcnt(0)
	v_mfma_f32_16x16x32_bf16 v[62:65], v[138:141], v[210:213], v[62:65]
	v_mfma_f32_16x16x32_bf16 v[58:61], v[174:177], v[210:213], v[58:61]
	v_mfma_f32_16x16x32_bf16 v[46:49], v[138:141], v[218:221], v[46:49]
	v_mfma_f32_16x16x32_bf16 v[42:45], v[174:177], v[218:221], v[42:45]
	v_mfma_f32_16x16x32_bf16 v[30:33], v[138:141], v[226:229], v[30:33]
	v_mfma_f32_16x16x32_bf16 v[26:29], v[174:177], v[226:229], v[26:29]
	v_mfma_f32_16x16x32_bf16 v[14:17], v[138:141], v[234:237], v[14:17]
	v_mfma_f32_16x16x32_bf16 v[10:13], v[174:177], v[234:237], v[10:13]
	v_mfma_f32_16x16x32_bf16 v[62:65], v[142:145], v[214:217], v[62:65]
	v_mfma_f32_16x16x32_bf16 v[58:61], v[180:183], v[214:217], v[58:61]
	v_mfma_f32_16x16x32_bf16 v[46:49], v[142:145], v[222:225], v[46:49]
	v_mfma_f32_16x16x32_bf16 v[42:45], v[180:183], v[222:225], v[42:45]
	v_mfma_f32_16x16x32_bf16 v[30:33], v[142:145], v[230:233], v[30:33]
	v_mfma_f32_16x16x32_bf16 v[26:29], v[180:183], v[230:233], v[26:29]
	v_mfma_f32_16x16x32_bf16 v[14:17], v[142:145], v[238:241], v[14:17]
	v_mfma_f32_16x16x32_bf16 v[10:13], v[180:183], v[238:241], v[10:13]
	v_mfma_f32_16x16x32_bf16 v[54:57], v[184:187], v[210:213], v[54:57]
	v_mfma_f32_16x16x32_bf16 v[50:53], v[192:195], v[210:213], v[50:53]
	v_mfma_f32_16x16x32_bf16 v[38:41], v[184:187], v[218:221], v[38:41]
	v_mfma_f32_16x16x32_bf16 v[34:37], v[192:195], v[218:221], v[34:37]
	v_mfma_f32_16x16x32_bf16 v[22:25], v[184:187], v[226:229], v[22:25]
	v_mfma_f32_16x16x32_bf16 v[18:21], v[192:195], v[226:229], v[18:21]
	v_mfma_f32_16x16x32_bf16 v[6:9], v[184:187], v[234:237], v[6:9]
	v_mfma_f32_16x16x32_bf16 v[2:5], v[192:195], v[234:237], v[2:5]
	v_mfma_f32_16x16x32_bf16 v[54:57], v[188:191], v[214:217], v[54:57]
	v_mfma_f32_16x16x32_bf16 v[50:53], v[196:199], v[214:217], v[50:53]
	v_mfma_f32_16x16x32_bf16 v[38:41], v[188:191], v[222:225], v[38:41]
	v_mfma_f32_16x16x32_bf16 v[34:37], v[196:199], v[222:225], v[34:37]
	v_mfma_f32_16x16x32_bf16 v[22:25], v[188:191], v[230:233], v[22:25]
	v_mfma_f32_16x16x32_bf16 v[18:21], v[196:199], v[230:233], v[18:21]
	v_mfma_f32_16x16x32_bf16 v[6:9], v[188:191], v[238:241], v[6:9]
	v_mfma_f32_16x16x32_bf16 v[2:5], v[196:199], v[238:241], v[2:5]
	s_barrier
	s_add_i32 s73, s73, 2
	s_add_u32 s54, s54, 0x100
	s_addc_u32 s55, s55, 0
	s_add_u32 s71, s71, 0x100
	s_addc_u32 s72, s72, 0
	s_cmp_gt_u32 s73, 13
	s_cbranch_scc0 .LBB0_1649
	s_and_b64 vcc, exec, s[20:21]
	s_cbranch_vccz .LBB0_1652
	s_barrier

.LBB0_1789:
	ds_read_b128 v[138:141], v1
	ds_read_b128 v[164:167], v1 offset:1024
	ds_read_b128 v[174:177], v1 offset:2048
	ds_read_b128 v[180:183], v1 offset:3072
	ds_read_b128 v[184:187], v157
	ds_read_b128 v[188:191], v157 offset:1024
	ds_read_b128 v[192:195], v157 offset:2048
	ds_read_b128 v[196:199], v157 offset:3072
	s_add_u32 s30, s38, 0xfffc0080
	s_addc_u32 s31, s39, -1
	s_cmp_eq_u32 s62, 12
	s_cselect_b32 s43, s6, s31
	s_cselect_b32 s42, s7, s30
	s_cselect_b32 s31, s21, s61
	s_cselect_b32 s30, s23, s60
	v_lshl_add_u64 v[142:143], s[38:39], 0, v[130:131]
	s_add_i32 m0, s44, 0xc000
	ds_read_b128 v[200:203], v159
	ds_read_b128 v[210:213], v159 offset:1024
	ds_read_b128 v[214:217], v159 offset:2048
	ds_read_b128 v[218:221], v159 offset:3072
	ds_read_b128 v[222:225], v159 offset:4096
	ds_read_b128 v[226:229], v159 offset:5120
	ds_read_b128 v[230:233], v159 offset:6144
	ds_read_b128 v[234:237], v159 offset:7168
	global_load_lds_dwordx4 v[142:143], off
	v_lshl_add_u64 v[142:143], s[38:39], 0, v[132:133]
	s_add_i32 m0, s44, 0xe000
	s_nop 0
	global_load_lds_dwordx4 v[142:143], off
	s_waitcnt vmcnt(8)
	s_waitcnt lgkmcnt(0)
	s_barrier
	s_waitcnt lgkmcnt(0)
	v_mfma_f32_16x16x32_bf16 v[126:129], v[138:141], v[200:203], v[126:129]
	v_mfma_f32_16x16x32_bf16 v[122:125], v[174:177], v[200:203], v[122:125]
	v_mfma_f32_16x16x32_bf16 v[110:113], v[138:141], v[214:217], v[110:113]
	v_mfma_f32_16x16x32_bf16 v[106:109], v[174:177], v[214:217], v[106:109]
	v_mfma_f32_16x16x32_bf16 v[94:97], v[138:141], v[222:225], v[94:97]
	v_mfma_f32_16x16x32_bf16 v[90:93], v[174:177], v[222:225], v[90:93]
	v_mfma_f32_16x16x32_bf16 v[78:81], v[138:141], v[230:233], v[78:81]
	v_mfma_f32_16x16x32_bf16 v[74:77], v[174:177], v[230:233], v[74:77]
	v_mfma_f32_16x16x32_bf16 v[126:129], v[164:167], v[210:213], v[126:129]
	v_mfma_f32_16x16x32_bf16 v[122:125], v[180:183], v[210:213], v[122:125]
	v_mfma_f32_16x16x32_bf16 v[110:113], v[164:167], v[218:221], v[110:113]
	v_mfma_f32_16x16x32_bf16 v[106:109], v[180:183], v[218:221], v[106:109]
	v_mfma_f32_16x16x32_bf16 v[94:97], v[164:167], v[226:229], v[94:97]
	v_mfma_f32_16x16x32_bf16 v[90:93], v[180:183], v[226:229], v[90:93]
	v_mfma_f32_16x16x32_bf16 v[78:81], v[164:167], v[234:237], v[78:81]
	v_mfma_f32_16x16x32_bf16 v[74:77], v[180:183], v[234:237], v[74:77]
	v_mfma_f32_16x16x32_bf16 v[118:121], v[184:187], v[200:203], v[118:121]
	v_mfma_f32_16x16x32_bf16 v[114:117], v[192:195], v[200:203], v[114:117]
	v_mfma_f32_16x16x32_bf16 v[102:105], v[184:187], v[214:217], v[102:105]
	v_mfma_f32_16x16x32_bf16 v[98:101], v[192:195], v[214:217], v[98:101]
	v_mfma_f32_16x16x32_bf16 v[86:89], v[184:187], v[222:225], v[86:89]
	v_mfma_f32_16x16x32_bf16 v[82:85], v[192:195], v[222:225], v[82:85]
	v_mfma_f32_16x16x32_bf16 v[70:73], v[184:187], v[230:233], v[70:73]
	v_mfma_f32_16x16x32_bf16 v[66:69], v[192:195], v[230:233], v[66:69]
	v_mfma_f32_16x16x32_bf16 v[118:121], v[188:191], v[210:213], v[118:121]
	v_mfma_f32_16x16x32_bf16 v[114:117], v[196:199], v[210:213], v[114:117]
	v_mfma_f32_16x16x32_bf16 v[102:105], v[188:191], v[218:221], v[102:105]
	v_mfma_f32_16x16x32_bf16 v[98:101], v[196:199], v[218:221], v[98:101]
	v_mfma_f32_16x16x32_bf16 v[86:89], v[188:191], v[226:229], v[86:89]
	v_mfma_f32_16x16x32_bf16 v[82:85], v[196:199], v[226:229], v[82:85]
	v_mfma_f32_16x16x32_bf16 v[70:73], v[188:191], v[234:237], v[70:73]
	v_mfma_f32_16x16x32_bf16 v[66:69], v[196:199], v[234:237], v[66:69]
	s_barrier
	s_add_i32 s33, s54, s11
	v_lshl_add_u64 v[142:143], s[30:31], 0, v[148:149]
	s_mov_b32 m0, s33
	ds_read_b128 v[200:203], v159 offset:16384
	ds_read_b128 v[210:213], v159 offset:17408
	ds_read_b128 v[214:217], v159 offset:18432
	ds_read_b128 v[218:221], v159 offset:19456
	ds_read_b128 v[222:225], v159 offset:20480
	ds_read_b128 v[226:229], v159 offset:21504
	ds_read_b128 v[230:233], v159 offset:22528
	ds_read_b128 v[234:237], v159 offset:23552
	global_load_lds_dwordx4 v[142:143], off
	s_add_i32 m0, s33, 0x2000
	s_add_u32 s64, s30, 0x40000
	v_lshl_add_u64 v[170:171], s[30:31], 0, v[152:153]
	s_addc_u32 s65, s31, 0
	s_add_i32 s33, s55, s11
	global_load_lds_dwordx4 v[170:171], off
	v_lshl_add_u64 v[238:239], s[64:65], 0, v[148:149]
	s_mov_b32 m0, s33
	v_lshl_add_u64 v[240:241], s[42:43], 0, v[150:151]
	global_load_lds_dwordx4 v[238:239], off
	v_lshl_add_u64 v[238:239], s[64:65], 0, v[152:153]
	s_add_i32 m0, s33, 0x2000
	s_nop 0
	global_load_lds_dwordx4 v[238:239], off
	v_lshl_add_u64 v[238:239], s[42:43], 0, v[146:147]
	s_mov_b32 m0, s44
	s_nop 0
	global_load_lds_dwordx4 v[238:239], off
	s_mov_b32 m0, s45
	s_nop 0
	global_load_lds_dwordx4 v[240:241], off
	s_waitcnt vmcnt(8)
	s_waitcnt lgkmcnt(0)
	s_barrier
	s_waitcnt lgkmcnt(0)
	v_mfma_f32_16x16x32_bf16 v[62:65], v[138:141], v[200:203], v[62:65]
	v_mfma_f32_16x16x32_bf16 v[58:61], v[174:177], v[200:203], v[58:61]
	v_mfma_f32_16x16x32_bf16 v[46:49], v[138:141], v[214:217], v[46:49]
	v_mfma_f32_16x16x32_bf16 v[42:45], v[174:177], v[214:217], v[42:45]
	v_mfma_f32_16x16x32_bf16 v[30:33], v[138:141], v[222:225], v[30:33]
	v_mfma_f32_16x16x32_bf16 v[26:29], v[174:177], v[222:225], v[26:29]
	v_mfma_f32_16x16x32_bf16 v[14:17], v[138:141], v[230:233], v[14:17]
	v_mfma_f32_16x16x32_bf16 v[10:13], v[174:177], v[230:233], v[10:13]
	v_mfma_f32_16x16x32_bf16 v[62:65], v[164:167], v[210:213], v[62:65]
	v_mfma_f32_16x16x32_bf16 v[58:61], v[180:183], v[210:213], v[58:61]
	v_mfma_f32_16x16x32_bf16 v[46:49], v[164:167], v[218:221], v[46:49]
	v_mfma_f32_16x16x32_bf16 v[42:45], v[180:183], v[218:221], v[42:45]
	v_mfma_f32_16x16x32_bf16 v[30:33], v[164:167], v[226:229], v[30:33]
	v_mfma_f32_16x16x32_bf16 v[26:29], v[180:183], v[226:229], v[26:29]
	v_mfma_f32_16x16x32_bf16 v[14:17], v[164:167], v[234:237], v[14:17]
	v_mfma_f32_16x16x32_bf16 v[10:13], v[180:183], v[234:237], v[10:13]
	v_mfma_f32_16x16x32_bf16 v[54:57], v[184:187], v[200:203], v[54:57]
	v_mfma_f32_16x16x32_bf16 v[50:53], v[192:195], v[200:203], v[50:53]
	v_mfma_f32_16x16x32_bf16 v[38:41], v[184:187], v[214:217], v[38:41]
	v_mfma_f32_16x16x32_bf16 v[34:37], v[192:195], v[214:217], v[34:37]
	v_mfma_f32_16x16x32_bf16 v[22:25], v[184:187], v[222:225], v[22:25]
	v_mfma_f32_16x16x32_bf16 v[18:21], v[192:195], v[222:225], v[18:21]
	v_mfma_f32_16x16x32_bf16 v[6:9], v[184:187], v[230:233], v[6:9]
	v_mfma_f32_16x16x32_bf16 v[2:5], v[192:195], v[230:233], v[2:5]
	v_mfma_f32_16x16x32_bf16 v[54:57], v[188:191], v[210:213], v[54:57]
	v_mfma_f32_16x16x32_bf16 v[50:53], v[196:199], v[210:213], v[50:53]
	v_mfma_f32_16x16x32_bf16 v[38:41], v[188:191], v[218:221], v[38:41]
	v_mfma_f32_16x16x32_bf16 v[34:37], v[196:199], v[218:221], v[34:37]
	v_mfma_f32_16x16x32_bf16 v[22:25], v[188:191], v[226:229], v[22:25]
	v_mfma_f32_16x16x32_bf16 v[18:21], v[196:199], v[226:229], v[18:21]
	v_mfma_f32_16x16x32_bf16 v[6:9], v[188:191], v[234:237], v[6:9]
	v_mfma_f32_16x16x32_bf16 v[2:5], v[196:199], v[234:237], v[2:5]
	s_barrier
	s_add_i32 s33, 0, 0x18000
	v_add_u32_e32 v163, s33, v145
	s_add_i32 s63, 0, 0x1c000
	ds_read_b128 v[138:141], v163
	ds_read_b128 v[164:167], v163 offset:1024
	ds_read_b128 v[174:177], v163 offset:2048
	ds_read_b128 v[180:183], v163 offset:3072
	v_add_u32_e32 v163, s63, v145
	ds_read_b128 v[184:187], v163
	ds_read_b128 v[188:191], v163 offset:1024
	ds_read_b128 v[192:195], v163 offset:2048
	ds_read_b128 v[196:199], v163 offset:3072
	s_add_u32 s42, s42, 0x40000
	s_addc_u32 s43, s43, 0
	s_mov_b32 m0, s48
	v_lshl_add_u64 v[242:243], s[42:43], 0, v[146:147]
	ds_read_b128 v[200:203], v159 offset:32768
	ds_read_b128 v[210:213], v159 offset:33792
	ds_read_b128 v[214:217], v159 offset:34816
	ds_read_b128 v[218:221], v159 offset:35840
	ds_read_b128 v[222:225], v159 offset:36864
	ds_read_b128 v[226:229], v159 offset:37888
	ds_read_b128 v[230:233], v159 offset:38912
	ds_read_b128 v[234:237], v159 offset:39936
	global_load_lds_dwordx4 v[242:243], off
	v_lshl_add_u64 v[242:243], s[42:43], 0, v[150:151]
	s_mov_b32 m0, s49
	s_nop 0
	global_load_lds_dwordx4 v[242:243], off
	s_waitcnt vmcnt(8)
	s_waitcnt lgkmcnt(0)
	s_barrier
	s_waitcnt lgkmcnt(0)
	v_mfma_f32_16x16x32_bf16 v[126:129], v[138:141], v[200:203], v[126:129]
	v_mfma_f32_16x16x32_bf16 v[122:125], v[174:177], v[200:203], v[122:125]
	v_mfma_f32_16x16x32_bf16 v[110:113], v[138:141], v[214:217], v[110:113]
	v_mfma_f32_16x16x32_bf16 v[106:109], v[174:177], v[214:217], v[106:109]
	v_mfma_f32_16x16x32_bf16 v[94:97], v[138:141], v[222:225], v[94:97]
	v_mfma_f32_16x16x32_bf16 v[90:93], v[174:177], v[222:225], v[90:93]
	v_mfma_f32_16x16x32_bf16 v[78:81], v[138:141], v[230:233], v[78:81]
	v_mfma_f32_16x16x32_bf16 v[74:77], v[174:177], v[230:233], v[74:77]
	v_mfma_f32_16x16x32_bf16 v[126:129], v[164:167], v[210:213], v[126:129]
	v_mfma_f32_16x16x32_bf16 v[122:125], v[180:183], v[210:213], v[122:125]
	v_mfma_f32_16x16x32_bf16 v[110:113], v[164:167], v[218:221], v[110:113]
	v_mfma_f32_16x16x32_bf16 v[106:109], v[180:183], v[218:221], v[106:109]
	v_mfma_f32_16x16x32_bf16 v[94:97], v[164:167], v[226:229], v[94:97]
	v_mfma_f32_16x16x32_bf16 v[90:93], v[180:183], v[226:229], v[90:93]
	v_mfma_f32_16x16x32_bf16 v[78:81], v[164:167], v[234:237], v[78:81]
	v_mfma_f32_16x16x32_bf16 v[74:77], v[180:183], v[234:237], v[74:77]
	v_mfma_f32_16x16x32_bf16 v[118:121], v[184:187], v[200:203], v[118:121]
	v_mfma_f32_16x16x32_bf16 v[114:117], v[192:195], v[200:203], v[114:117]
	v_mfma_f32_16x16x32_bf16 v[102:105], v[184:187], v[214:217], v[102:105]
	v_mfma_f32_16x16x32_bf16 v[98:101], v[192:195], v[214:217], v[98:101]
	v_mfma_f32_16x16x32_bf16 v[86:89], v[184:187], v[222:225], v[86:89]
	v_mfma_f32_16x16x32_bf16 v[82:85], v[192:195], v[222:225], v[82:85]
	v_mfma_f32_16x16x32_bf16 v[70:73], v[184:187], v[230:233], v[70:73]
	v_mfma_f32_16x16x32_bf16 v[66:69], v[192:195], v[230:233], v[66:69]
	v_mfma_f32_16x16x32_bf16 v[118:121], v[188:191], v[210:213], v[118:121]
	v_mfma_f32_16x16x32_bf16 v[114:117], v[196:199], v[210:213], v[114:117]
	v_mfma_f32_16x16x32_bf16 v[102:105], v[188:191], v[218:221], v[102:105]
	v_mfma_f32_16x16x32_bf16 v[98:101], v[196:199], v[218:221], v[98:101]
	v_mfma_f32_16x16x32_bf16 v[86:89], v[188:191], v[226:229], v[86:89]
	v_mfma_f32_16x16x32_bf16 v[82:85], v[196:199], v[226:229], v[82:85]
	v_mfma_f32_16x16x32_bf16 v[70:73], v[188:191], v[234:237], v[70:73]
	v_mfma_f32_16x16x32_bf16 v[66:69], v[196:199], v[234:237], v[66:69]
	s_barrier
	s_add_i32 s33, s33, s11
	v_lshl_add_u64 v[142:143], v[142:143], 0, s[14:15]
	s_mov_b32 m0, s33
	ds_read_b128 v[200:203], v159 offset:49152
	ds_read_b128 v[210:213], v159 offset:50176
	ds_read_b128 v[214:217], v159 offset:51200
	ds_read_b128 v[218:221], v159 offset:52224
	ds_read_b128 v[222:225], v159 offset:53248
	ds_read_b128 v[226:229], v159 offset:54272
	ds_read_b128 v[230:233], v159 offset:55296
	ds_read_b128 v[234:237], v159 offset:56320
	global_load_lds_dwordx4 v[142:143], off
	s_add_i32 m0, s33, 0x2000
	s_add_u32 s30, s30, 0x40080
	v_lshl_add_u64 v[142:143], v[170:171], 0, s[14:15]
	s_addc_u32 s31, s31, 0
	s_add_i32 s33, s63, s11
	global_load_lds_dwordx4 v[142:143], off
	v_lshl_add_u64 v[142:143], s[30:31], 0, v[148:149]
	s_mov_b32 m0, s33
	s_nop 0
	global_load_lds_dwordx4 v[142:143], off
	v_lshl_add_u64 v[142:143], s[30:31], 0, v[152:153]
	s_add_i32 m0, s33, 0x2000
	s_nop 0
	global_load_lds_dwordx4 v[142:143], off
	v_lshl_add_u64 v[142:143], v[238:239], 0, s[14:15]
	s_mov_b32 m0, s51
	s_nop 0
	global_load_lds_dwordx4 v[142:143], off
	v_lshl_add_u64 v[142:143], v[240:241], 0, s[14:15]
	s_mov_b32 m0, s52
	s_nop 0
	global_load_lds_dwordx4 v[142:143], off
	s_waitcnt vmcnt(8)
	s_waitcnt lgkmcnt(0)
	s_barrier
	s_waitcnt lgkmcnt(0)
	v_mfma_f32_16x16x32_bf16 v[62:65], v[138:141], v[200:203], v[62:65]
	v_mfma_f32_16x16x32_bf16 v[58:61], v[174:177], v[200:203], v[58:61]
	v_mfma_f32_16x16x32_bf16 v[46:49], v[138:141], v[214:217], v[46:49]
	v_mfma_f32_16x16x32_bf16 v[42:45], v[174:177], v[214:217], v[42:45]
	v_mfma_f32_16x16x32_bf16 v[30:33], v[138:141], v[222:225], v[30:33]
	v_mfma_f32_16x16x32_bf16 v[26:29], v[174:177], v[222:225], v[26:29]
	v_mfma_f32_16x16x32_bf16 v[14:17], v[138:141], v[230:233], v[14:17]
	v_mfma_f32_16x16x32_bf16 v[10:13], v[174:177], v[230:233], v[10:13]
	v_mfma_f32_16x16x32_bf16 v[62:65], v[164:167], v[210:213], v[62:65]
	v_mfma_f32_16x16x32_bf16 v[58:61], v[180:183], v[210:213], v[58:61]
	v_mfma_f32_16x16x32_bf16 v[46:49], v[164:167], v[218:221], v[46:49]
	v_mfma_f32_16x16x32_bf16 v[42:45], v[180:183], v[218:221], v[42:45]
	v_mfma_f32_16x16x32_bf16 v[30:33], v[164:167], v[226:229], v[30:33]
	v_mfma_f32_16x16x32_bf16 v[26:29], v[180:183], v[226:229], v[26:29]
	v_mfma_f32_16x16x32_bf16 v[14:17], v[164:167], v[234:237], v[14:17]
	v_mfma_f32_16x16x32_bf16 v[10:13], v[180:183], v[234:237], v[10:13]
	v_mfma_f32_16x16x32_bf16 v[54:57], v[184:187], v[200:203], v[54:57]
	v_mfma_f32_16x16x32_bf16 v[50:53], v[192:195], v[200:203], v[50:53]
	v_mfma_f32_16x16x32_bf16 v[38:41], v[184:187], v[214:217], v[38:41]
	v_mfma_f32_16x16x32_bf16 v[34:37], v[192:195], v[214:217], v[34:37]
	v_mfma_f32_16x16x32_bf16 v[22:25], v[184:187], v[222:225], v[22:25]
	v_mfma_f32_16x16x32_bf16 v[18:21], v[192:195], v[222:225], v[18:21]
	v_mfma_f32_16x16x32_bf16 v[6:9], v[184:187], v[230:233], v[6:9]
	v_mfma_f32_16x16x32_bf16 v[2:5], v[192:195], v[230:233], v[2:5]
	v_mfma_f32_16x16x32_bf16 v[54:57], v[188:191], v[210:213], v[54:57]
	v_mfma_f32_16x16x32_bf16 v[50:53], v[196:199], v[210:213], v[50:53]
	v_mfma_f32_16x16x32_bf16 v[38:41], v[188:191], v[218:221], v[38:41]
	v_mfma_f32_16x16x32_bf16 v[34:37], v[196:199], v[218:221], v[34:37]
	v_mfma_f32_16x16x32_bf16 v[22:25], v[188:191], v[226:229], v[22:25]
	v_mfma_f32_16x16x32_bf16 v[18:21], v[196:199], v[226:229], v[18:21]
	v_mfma_f32_16x16x32_bf16 v[6:9], v[188:191], v[234:237], v[6:9]
	v_mfma_f32_16x16x32_bf16 v[2:5], v[196:199], v[234:237], v[2:5]
	s_barrier
	s_add_i32 s62, s62, 2
	s_add_u32 s38, s38, 0x100
	s_addc_u32 s39, s39, 0
	s_add_u32 s60, s60, 0x100
	s_addc_u32 s61, s61, 0
	s_cmp_gt_u32 s62, 13
	s_cbranch_scc0 .LBB0_1789
	s_and_b64 vcc, exec, s[18:19]
	s_cbranch_vccz .LBB0_1792
	s_barrier

.LBB0_1869:
	ds_read_b128 v[136:139], v145
	ds_read_b128 v[148:151], v145 offset:1024
	ds_read_b128 v[152:155], v145 offset:2048
	ds_read_b128 v[164:167], v145 offset:3072
	ds_read_b128 v[168:171], v146
	ds_read_b128 v[172:175], v146 offset:1024
	ds_read_b128 v[176:179], v146 offset:2048
	ds_read_b128 v[180:183], v146 offset:3072
	s_add_u32 s28, s24, 0xfff50080
	s_addc_u32 s29, s25, -1
	s_cmp_eq_u32 s57, 40
	s_cselect_b32 s31, s5, s29
	s_cselect_b32 s30, s4, s28
	s_cselect_b32 s29, s23, s56
	s_cselect_b32 s28, s22, s55
	v_lshl_add_u64 v[140:141], s[24:25], 0, v[128:129]
	s_add_i32 m0, s35, 0xc000
	ds_read_b128 v[184:187], v147
	ds_read_b128 v[188:191], v147 offset:1024
	ds_read_b128 v[192:195], v147 offset:2048
	ds_read_b128 v[196:199], v147 offset:3072
	ds_read_b128 v[200:203], v147 offset:4096
	ds_read_b128 v[204:207], v147 offset:5120
	ds_read_b128 v[208:211], v147 offset:6144
	ds_read_b128 v[212:215], v147 offset:7168
	global_load_lds_dwordx4 v[140:141], off
	v_lshl_add_u64 v[140:141], s[24:25], 0, v[130:131]
	s_add_i32 m0, s35, 0xe000
	s_nop 0
	global_load_lds_dwordx4 v[140:141], off
	s_waitcnt vmcnt(8)
	s_waitcnt lgkmcnt(0)
	s_barrier
	s_waitcnt lgkmcnt(0)
	v_mfma_f32_16x16x32_bf16 v[124:127], v[136:139], v[184:187], v[124:127]
	v_mfma_f32_16x16x32_bf16 v[120:123], v[152:155], v[184:187], v[120:123]
	v_mfma_f32_16x16x32_bf16 v[108:111], v[136:139], v[192:195], v[108:111]
	v_mfma_f32_16x16x32_bf16 v[104:107], v[152:155], v[192:195], v[104:107]
	v_mfma_f32_16x16x32_bf16 v[92:95], v[136:139], v[200:203], v[92:95]
	v_mfma_f32_16x16x32_bf16 v[88:91], v[152:155], v[200:203], v[88:91]
	v_mfma_f32_16x16x32_bf16 v[76:79], v[136:139], v[208:211], v[76:79]
	v_mfma_f32_16x16x32_bf16 v[72:75], v[152:155], v[208:211], v[72:75]
	v_mfma_f32_16x16x32_bf16 v[124:127], v[148:151], v[188:191], v[124:127]
	v_mfma_f32_16x16x32_bf16 v[120:123], v[164:167], v[188:191], v[120:123]
	v_mfma_f32_16x16x32_bf16 v[108:111], v[148:151], v[196:199], v[108:111]
	v_mfma_f32_16x16x32_bf16 v[104:107], v[164:167], v[196:199], v[104:107]
	v_mfma_f32_16x16x32_bf16 v[92:95], v[148:151], v[204:207], v[92:95]
	v_mfma_f32_16x16x32_bf16 v[88:91], v[164:167], v[204:207], v[88:91]
	v_mfma_f32_16x16x32_bf16 v[76:79], v[148:151], v[212:215], v[76:79]
	v_mfma_f32_16x16x32_bf16 v[72:75], v[164:167], v[212:215], v[72:75]
	v_mfma_f32_16x16x32_bf16 v[116:119], v[168:171], v[184:187], v[116:119]
	v_mfma_f32_16x16x32_bf16 v[112:115], v[176:179], v[184:187], v[112:115]
	v_mfma_f32_16x16x32_bf16 v[100:103], v[168:171], v[192:195], v[100:103]
	v_mfma_f32_16x16x32_bf16 v[96:99], v[176:179], v[192:195], v[96:99]
	v_mfma_f32_16x16x32_bf16 v[84:87], v[168:171], v[200:203], v[84:87]
	v_mfma_f32_16x16x32_bf16 v[80:83], v[176:179], v[200:203], v[80:83]
	v_mfma_f32_16x16x32_bf16 v[68:71], v[168:171], v[208:211], v[68:71]
	v_mfma_f32_16x16x32_bf16 v[64:67], v[176:179], v[208:211], v[64:67]
	v_mfma_f32_16x16x32_bf16 v[116:119], v[172:175], v[188:191], v[116:119]
	v_mfma_f32_16x16x32_bf16 v[112:115], v[180:183], v[188:191], v[112:115]
	v_mfma_f32_16x16x32_bf16 v[100:103], v[172:175], v[196:199], v[100:103]
	v_mfma_f32_16x16x32_bf16 v[96:99], v[180:183], v[196:199], v[96:99]
	v_mfma_f32_16x16x32_bf16 v[84:87], v[172:175], v[204:207], v[84:87]
	v_mfma_f32_16x16x32_bf16 v[80:83], v[180:183], v[204:207], v[80:83]
	v_mfma_f32_16x16x32_bf16 v[68:71], v[172:175], v[212:215], v[68:71]
	v_mfma_f32_16x16x32_bf16 v[64:67], v[180:183], v[212:215], v[64:67]
	s_barrier
	s_add_i32 s58, s45, s34
	v_lshl_add_u64 v[140:141], s[28:29], 0, v[158:159]
	s_mov_b32 m0, s58
	ds_read_b128 v[184:187], v147 offset:16384
	ds_read_b128 v[188:191], v147 offset:17408
	ds_read_b128 v[192:195], v147 offset:18432
	ds_read_b128 v[196:199], v147 offset:19456
	ds_read_b128 v[200:203], v147 offset:20480
	ds_read_b128 v[204:207], v147 offset:21504
	ds_read_b128 v[208:211], v147 offset:22528
	ds_read_b128 v[212:215], v147 offset:23552
	global_load_lds_dwordx4 v[140:141], off
	s_add_i32 m0, s58, 0x2000
	s_add_u32 s58, s28, 0xb0000
	v_lshl_add_u64 v[216:217], s[28:29], 0, v[162:163]
	s_addc_u32 s59, s29, 0
	s_add_i32 s60, s46, s34
	global_load_lds_dwordx4 v[216:217], off
	v_lshl_add_u64 v[218:219], s[58:59], 0, v[158:159]
	s_mov_b32 m0, s60
	v_lshl_add_u64 v[220:221], s[30:31], 0, v[160:161]
	global_load_lds_dwordx4 v[218:219], off
	v_lshl_add_u64 v[218:219], s[58:59], 0, v[162:163]
	s_add_i32 m0, s60, 0x2000
	s_nop 0
	global_load_lds_dwordx4 v[218:219], off
	v_lshl_add_u64 v[218:219], s[30:31], 0, v[156:157]
	s_mov_b32 m0, s35
	s_nop 0
	global_load_lds_dwordx4 v[218:219], off
	s_mov_b32 m0, s38
	s_nop 0
	global_load_lds_dwordx4 v[220:221], off
	s_waitcnt vmcnt(8)
	s_waitcnt lgkmcnt(0)
	s_barrier
	s_waitcnt lgkmcnt(0)
	v_mfma_f32_16x16x32_bf16 v[60:63], v[136:139], v[184:187], v[60:63]
	v_mfma_f32_16x16x32_bf16 v[56:59], v[152:155], v[184:187], v[56:59]
	v_mfma_f32_16x16x32_bf16 v[44:47], v[136:139], v[192:195], v[44:47]
	v_mfma_f32_16x16x32_bf16 v[40:43], v[152:155], v[192:195], v[40:43]
	v_mfma_f32_16x16x32_bf16 v[28:31], v[136:139], v[200:203], v[28:31]
	v_mfma_f32_16x16x32_bf16 v[24:27], v[152:155], v[200:203], v[24:27]
	v_mfma_f32_16x16x32_bf16 v[12:15], v[136:139], v[208:211], v[12:15]
	v_mfma_f32_16x16x32_bf16 v[8:11], v[152:155], v[208:211], v[8:11]
	v_mfma_f32_16x16x32_bf16 v[60:63], v[148:151], v[188:191], v[60:63]
	v_mfma_f32_16x16x32_bf16 v[56:59], v[164:167], v[188:191], v[56:59]
	v_mfma_f32_16x16x32_bf16 v[44:47], v[148:151], v[196:199], v[44:47]
	v_mfma_f32_16x16x32_bf16 v[40:43], v[164:167], v[196:199], v[40:43]
	v_mfma_f32_16x16x32_bf16 v[28:31], v[148:151], v[204:207], v[28:31]
	v_mfma_f32_16x16x32_bf16 v[24:27], v[164:167], v[204:207], v[24:27]
	v_mfma_f32_16x16x32_bf16 v[12:15], v[148:151], v[212:215], v[12:15]
	v_mfma_f32_16x16x32_bf16 v[8:11], v[164:167], v[212:215], v[8:11]
	v_mfma_f32_16x16x32_bf16 v[52:55], v[168:171], v[184:187], v[52:55]
	v_mfma_f32_16x16x32_bf16 v[48:51], v[176:179], v[184:187], v[48:51]
	v_mfma_f32_16x16x32_bf16 v[36:39], v[168:171], v[192:195], v[36:39]
	v_mfma_f32_16x16x32_bf16 v[32:35], v[176:179], v[192:195], v[32:35]
	v_mfma_f32_16x16x32_bf16 v[20:23], v[168:171], v[200:203], v[20:23]
	v_mfma_f32_16x16x32_bf16 v[16:19], v[176:179], v[200:203], v[16:19]
	v_mfma_f32_16x16x32_bf16 v[4:7], v[168:171], v[208:211], v[4:7]
	v_mfma_f32_16x16x32_bf16 v[0:3], v[176:179], v[208:211], v[0:3]
	v_mfma_f32_16x16x32_bf16 v[52:55], v[172:175], v[188:191], v[52:55]
	v_mfma_f32_16x16x32_bf16 v[48:51], v[180:183], v[188:191], v[48:51]
	v_mfma_f32_16x16x32_bf16 v[36:39], v[172:175], v[196:199], v[36:39]
	v_mfma_f32_16x16x32_bf16 v[32:35], v[180:183], v[196:199], v[32:35]
	v_mfma_f32_16x16x32_bf16 v[20:23], v[172:175], v[204:207], v[20:23]
	v_mfma_f32_16x16x32_bf16 v[16:19], v[180:183], v[204:207], v[16:19]
	v_mfma_f32_16x16x32_bf16 v[4:7], v[172:175], v[212:215], v[4:7]
	v_mfma_f32_16x16x32_bf16 v[0:3], v[180:183], v[212:215], v[0:3]
	s_barrier
	s_add_i32 s58, 0, 0x18000
	s_add_i32 s59, 0, 0x1c000
	v_add_u32_e32 v164, s58, v143
	v_add_u32_e32 v180, s59, v143
	ds_read_b128 v[136:139], v164
	ds_read_b128 v[148:151], v164 offset:1024
	ds_read_b128 v[152:155], v164 offset:2048
	ds_read_b128 v[164:167], v164 offset:3072
	ds_read_b128 v[168:171], v180
	ds_read_b128 v[172:175], v180 offset:1024
	ds_read_b128 v[176:179], v180 offset:2048
	ds_read_b128 v[180:183], v180 offset:3072
	s_add_u32 s30, s30, 0xb0000
	s_addc_u32 s31, s31, 0
	s_mov_b32 m0, s39
	v_lshl_add_u64 v[222:223], s[30:31], 0, v[156:157]
	ds_read_b128 v[184:187], v147 offset:32768
	ds_read_b128 v[188:191], v147 offset:33792
	ds_read_b128 v[192:195], v147 offset:34816
	ds_read_b128 v[196:199], v147 offset:35840
	ds_read_b128 v[200:203], v147 offset:36864
	ds_read_b128 v[204:207], v147 offset:37888
	ds_read_b128 v[208:211], v147 offset:38912
	ds_read_b128 v[212:215], v147 offset:39936
	global_load_lds_dwordx4 v[222:223], off
	v_lshl_add_u64 v[222:223], s[30:31], 0, v[160:161]
	s_mov_b32 m0, s40
	s_nop 0
	global_load_lds_dwordx4 v[222:223], off
	s_waitcnt vmcnt(8)
	s_waitcnt lgkmcnt(0)
	s_barrier
	s_waitcnt lgkmcnt(0)
	v_mfma_f32_16x16x32_bf16 v[124:127], v[136:139], v[184:187], v[124:127]
	v_mfma_f32_16x16x32_bf16 v[120:123], v[152:155], v[184:187], v[120:123]
	v_mfma_f32_16x16x32_bf16 v[108:111], v[136:139], v[192:195], v[108:111]
	v_mfma_f32_16x16x32_bf16 v[104:107], v[152:155], v[192:195], v[104:107]
	v_mfma_f32_16x16x32_bf16 v[92:95], v[136:139], v[200:203], v[92:95]
	v_mfma_f32_16x16x32_bf16 v[88:91], v[152:155], v[200:203], v[88:91]
	v_mfma_f32_16x16x32_bf16 v[76:79], v[136:139], v[208:211], v[76:79]
	v_mfma_f32_16x16x32_bf16 v[72:75], v[152:155], v[208:211], v[72:75]
	v_mfma_f32_16x16x32_bf16 v[124:127], v[148:151], v[188:191], v[124:127]
	v_mfma_f32_16x16x32_bf16 v[120:123], v[164:167], v[188:191], v[120:123]
	v_mfma_f32_16x16x32_bf16 v[108:111], v[148:151], v[196:199], v[108:111]
	v_mfma_f32_16x16x32_bf16 v[104:107], v[164:167], v[196:199], v[104:107]
	v_mfma_f32_16x16x32_bf16 v[92:95], v[148:151], v[204:207], v[92:95]
	v_mfma_f32_16x16x32_bf16 v[88:91], v[164:167], v[204:207], v[88:91]
	v_mfma_f32_16x16x32_bf16 v[76:79], v[148:151], v[212:215], v[76:79]
	v_mfma_f32_16x16x32_bf16 v[72:75], v[164:167], v[212:215], v[72:75]
	v_mfma_f32_16x16x32_bf16 v[116:119], v[168:171], v[184:187], v[116:119]
	v_mfma_f32_16x16x32_bf16 v[112:115], v[176:179], v[184:187], v[112:115]
	v_mfma_f32_16x16x32_bf16 v[100:103], v[168:171], v[192:195], v[100:103]
	v_mfma_f32_16x16x32_bf16 v[96:99], v[176:179], v[192:195], v[96:99]
	v_mfma_f32_16x16x32_bf16 v[84:87], v[168:171], v[200:203], v[84:87]
	v_mfma_f32_16x16x32_bf16 v[80:83], v[176:179], v[200:203], v[80:83]
	v_mfma_f32_16x16x32_bf16 v[68:71], v[168:171], v[208:211], v[68:71]
	v_mfma_f32_16x16x32_bf16 v[64:67], v[176:179], v[208:211], v[64:67]
	v_mfma_f32_16x16x32_bf16 v[116:119], v[172:175], v[188:191], v[116:119]
	v_mfma_f32_16x16x32_bf16 v[112:115], v[180:183], v[188:191], v[112:115]
	v_mfma_f32_16x16x32_bf16 v[100:103], v[172:175], v[196:199], v[100:103]
	v_mfma_f32_16x16x32_bf16 v[96:99], v[180:183], v[196:199], v[96:99]
	v_mfma_f32_16x16x32_bf16 v[84:87], v[172:175], v[204:207], v[84:87]
	v_mfma_f32_16x16x32_bf16 v[80:83], v[180:183], v[204:207], v[80:83]
	v_mfma_f32_16x16x32_bf16 v[68:71], v[172:175], v[212:215], v[68:71]
	v_mfma_f32_16x16x32_bf16 v[64:67], v[180:183], v[212:215], v[64:67]
	s_barrier
	s_add_i32 s30, s58, s34
	v_lshl_add_u64 v[140:141], v[140:141], 0, s[10:11]
	s_mov_b32 m0, s30
	ds_read_b128 v[184:187], v147 offset:49152
	ds_read_b128 v[188:191], v147 offset:50176
	ds_read_b128 v[192:195], v147 offset:51200
	ds_read_b128 v[196:199], v147 offset:52224
	ds_read_b128 v[200:203], v147 offset:53248
	ds_read_b128 v[204:207], v147 offset:54272
	ds_read_b128 v[208:211], v147 offset:55296
	ds_read_b128 v[212:215], v147 offset:56320
	global_load_lds_dwordx4 v[140:141], off
	s_add_i32 m0, s30, 0x2000
	s_add_u32 s28, s28, 0xb0080
	v_lshl_add_u64 v[140:141], v[216:217], 0, s[10:11]
	s_addc_u32 s29, s29, 0
	s_add_i32 s30, s59, s34
	global_load_lds_dwordx4 v[140:141], off
	v_lshl_add_u64 v[140:141], s[28:29], 0, v[158:159]
	s_mov_b32 m0, s30
	s_nop 0
	global_load_lds_dwordx4 v[140:141], off
	v_lshl_add_u64 v[140:141], s[28:29], 0, v[162:163]
	s_add_i32 m0, s30, 0x2000
	s_nop 0
	global_load_lds_dwordx4 v[140:141], off
	v_lshl_add_u64 v[140:141], v[218:219], 0, s[10:11]
	s_mov_b32 m0, s42
	s_nop 0
	global_load_lds_dwordx4 v[140:141], off
	v_lshl_add_u64 v[140:141], v[220:221], 0, s[10:11]
	s_mov_b32 m0, s43
	s_nop 0
	global_load_lds_dwordx4 v[140:141], off
	s_waitcnt vmcnt(8)
	s_waitcnt lgkmcnt(0)
	s_barrier
	s_waitcnt lgkmcnt(0)
	v_mfma_f32_16x16x32_bf16 v[60:63], v[136:139], v[184:187], v[60:63]
	v_mfma_f32_16x16x32_bf16 v[56:59], v[152:155], v[184:187], v[56:59]
	v_mfma_f32_16x16x32_bf16 v[44:47], v[136:139], v[192:195], v[44:47]
	v_mfma_f32_16x16x32_bf16 v[40:43], v[152:155], v[192:195], v[40:43]
	v_mfma_f32_16x16x32_bf16 v[28:31], v[136:139], v[200:203], v[28:31]
	v_mfma_f32_16x16x32_bf16 v[24:27], v[152:155], v[200:203], v[24:27]
	v_mfma_f32_16x16x32_bf16 v[12:15], v[136:139], v[208:211], v[12:15]
	v_mfma_f32_16x16x32_bf16 v[8:11], v[152:155], v[208:211], v[8:11]
	v_mfma_f32_16x16x32_bf16 v[60:63], v[148:151], v[188:191], v[60:63]
	v_mfma_f32_16x16x32_bf16 v[56:59], v[164:167], v[188:191], v[56:59]
	v_mfma_f32_16x16x32_bf16 v[44:47], v[148:151], v[196:199], v[44:47]
	v_mfma_f32_16x16x32_bf16 v[40:43], v[164:167], v[196:199], v[40:43]
	v_mfma_f32_16x16x32_bf16 v[28:31], v[148:151], v[204:207], v[28:31]
	v_mfma_f32_16x16x32_bf16 v[24:27], v[164:167], v[204:207], v[24:27]
	v_mfma_f32_16x16x32_bf16 v[12:15], v[148:151], v[212:215], v[12:15]
	v_mfma_f32_16x16x32_bf16 v[8:11], v[164:167], v[212:215], v[8:11]
	v_mfma_f32_16x16x32_bf16 v[52:55], v[168:171], v[184:187], v[52:55]
	v_mfma_f32_16x16x32_bf16 v[48:51], v[176:179], v[184:187], v[48:51]
	v_mfma_f32_16x16x32_bf16 v[36:39], v[168:171], v[192:195], v[36:39]
	v_mfma_f32_16x16x32_bf16 v[32:35], v[176:179], v[192:195], v[32:35]
	v_mfma_f32_16x16x32_bf16 v[20:23], v[168:171], v[200:203], v[20:23]
	v_mfma_f32_16x16x32_bf16 v[16:19], v[176:179], v[200:203], v[16:19]
	v_mfma_f32_16x16x32_bf16 v[4:7], v[168:171], v[208:211], v[4:7]
	v_mfma_f32_16x16x32_bf16 v[0:3], v[176:179], v[208:211], v[0:3]
	v_mfma_f32_16x16x32_bf16 v[52:55], v[172:175], v[188:191], v[52:55]
	v_mfma_f32_16x16x32_bf16 v[48:51], v[180:183], v[188:191], v[48:51]
	v_mfma_f32_16x16x32_bf16 v[36:39], v[172:175], v[196:199], v[36:39]
	v_mfma_f32_16x16x32_bf16 v[32:35], v[180:183], v[196:199], v[32:35]
	v_mfma_f32_16x16x32_bf16 v[20:23], v[172:175], v[204:207], v[20:23]
	v_mfma_f32_16x16x32_bf16 v[16:19], v[180:183], v[204:207], v[16:19]
	v_mfma_f32_16x16x32_bf16 v[4:7], v[172:175], v[212:215], v[4:7]
	v_mfma_f32_16x16x32_bf16 v[0:3], v[180:183], v[212:215], v[0:3]
	s_barrier
	s_add_i32 s57, s57, 2
	s_add_u32 s24, s24, 0x100
	s_addc_u32 s25, s25, 0
	s_add_u32 s55, s55, 0x100
	s_addc_u32 s56, s56, 0
	s_cmp_gt_u32 s57, 41
	s_cbranch_scc0 .LBB0_1869
	s_and_b64 vcc, exec, s[12:13]
	s_cbranch_vccnz .LBB0_1877
	s_cmp_gt_i32 s53, 41
	s_mov_b64 s[24:25], -1
	s_cbranch_scc1 .LBB0_1878
